# GEMM K-loops: priority raise moved in front of the segment barrier and the redundant lgkmcnt wait behind it dropped, so the first MFMA follows the barrier directly
# speedup vs baseline: 1.0137x; 1.0137x over previous
; #define PG8_STAGE(bufoff, gbase, voff) do { _Pragma("unroll") for (int _i = 0; _i < 2; ++_i) \
;         __builtin_amdgcn_global_load_lds((const unsigned*)((const char*)(gbase) + (voff)[_i]), (PG8_LAS unsigned*)(lds + (bufoff) + ldsw + _i * 8192), 16, 0, 0); } while (0)
; #define PG8_LDA(dst, b, h) do { _Pragma("unroll") for (int m = 0; m < 4; ++m) _Pragma("unroll") for (int k = 0; k < 2; ++k) dst[m][k] = *(const PG8_LAS bf16x8*)(lds + PG8_SA(b, h) + aoff + m * 2048 + k * 1024); } while (0)
; #define PG8_LDB(dst, b, h) do { _Pragma("unroll") for (int n = 0; n < 2; ++n) _Pragma("unroll") for (int k = 0; k < 2; ++k) dst[n][k] = *(const PG8_LAS bf16x8*)(lds + PG8_SB(b, h) + boff + n * 2048 + k * 1024); } while (0)
; #define PG8_WAIT_V(n) asm volatile("s_waitcnt vmcnt(" #n ")" ::: "memory")
; #define PG8_WAIT_L(n) asm volatile("s_waitcnt lgkmcnt(" #n ")" ::: "memory")
; #define PG8_BAR __builtin_amdgcn_s_barrier()
; #define PG8_SCHED __builtin_amdgcn_sched_barrier(0)
; template <class Epi, class Sched, bool ALIGN_EPI = false, bool SP2 = false>
; __device__ __forceinline__ void gemm_phase(PG8_LAS unsigned char* lds, const Gemm g, const Sched& S, const Epi& E) {
;     ...
;         const char* nA = has_next ? (const char*)g.A + S.a_byte(nxt, K) : cA; const char* nB = has_next ? (const char*)g.Bt + (size_t)nxt.pn * tstep : cB;
;         for (int t = 0; t < nt; t += 2) {
;             const bool last = (t == nt - 2);
;             const char* a1 = cA + (size_t)(t + 1) * kstep;
;             const char* a2 = last ? nA : cA + (size_t)(t + 2) * kstep; const char* b2 = last ? nB : cB + (size_t)(t + 2) * kstep;
;             const char* a3 = a2 + kstep; const char* b3 = b2 + kstep;
;             if (last && has_next) S.a_ready(nxt);
;             if constexpr (SP2) {
;             PG8_LDB(B0, 0, 0); PG8_LDB(B1, 0, 1); PG8_SCHED; PG8_LDA(At, 0, 0); PG8_STAGE(PG8_SA(1, 1), a1 + hstep, voffA);
;             PG8_WAIT_V(8); PG8_WAIT_L(0); PG8_BAR; PG8_MMA(0, 0, At, B0); PG8_MMA(0, 1, At, B1); PG8_BAR; PG8_SCHED;
;             PG8_LDA(At, 0, 1); PG8_STAGE(PG8_SB(0, 0), b2, voffB); PG8_STAGE(PG8_SB(0, 1), b2 + hstep, voffB); PG8_STAGE(PG8_SA(0, 0), a2, voffA);
;             PG8_WAIT_V(8); PG8_WAIT_L(0); PG8_BAR; PG8_MMA(1, 0, At, B0); PG8_MMA(1, 1, At, B1); PG8_BAR; PG8_SCHED;
.LBB0_62:
	s_add_i32 s79, s58, 2
	s_add_u32 s18, s56, 0x80
	s_addc_u32 s19, s57, 0
	s_add_i32 s86, 0, 0x10000
	s_cmp_eq_u32 s72, s58
	s_cselect_b32 s59, s9, s19
	s_cselect_b32 s58, s8, s18
	s_cselect_b32 s85, s55, s78
	s_cselect_b32 s84, s54, s38
	s_add_i32 s18, 0, 0x14000
	v_add_u32_e32 v76, s86, v248
	v_add_u32_e32 v156, s18, v248
	ds_read_b128 v[64:67], v76
	ds_read_b128 v[68:71], v76 offset:1024
	ds_read_b128 v[72:75], v76 offset:2048
	ds_read_b128 v[76:79], v76 offset:3072
	ds_read_b128 v[144:147], v156
	ds_read_b128 v[148:151], v156 offset:1024
	ds_read_b128 v[152:155], v156 offset:2048
	ds_read_b128 v[156:159], v156 offset:3072
	v_lshl_add_u64 v[192:193], s[56:57], 0, v[224:225]
	s_add_i32 m0, s64, 0xc000
	ds_read_b128 v[160:163], v250
	ds_read_b128 v[164:167], v250 offset:1024
	ds_read_b128 v[168:171], v250 offset:2048
	ds_read_b128 v[172:175], v250 offset:3072
	ds_read_b128 v[176:179], v250 offset:4096
	ds_read_b128 v[180:183], v250 offset:5120
	ds_read_b128 v[184:187], v250 offset:6144
	ds_read_b128 v[188:191], v250 offset:7168
	global_load_lds_dwordx4 v[192:193], off
	v_lshl_add_u64 v[192:193], s[56:57], 0, v[226:227]
	s_add_i32 m0, s64, 0xe000
	s_nop 0
	global_load_lds_dwordx4 v[192:193], off
	s_waitcnt vmcnt(8)
	s_waitcnt lgkmcnt(0)
	s_setprio 1
	s_barrier
	v_mfma_f32_16x16x32_bf16 v[140:143], v[64:67], v[160:163], v[140:143]
	v_mfma_f32_16x16x32_bf16 v[136:139], v[72:75], v[160:163], v[136:139]
	v_mfma_f32_16x16x32_bf16 v[124:127], v[64:67], v[168:171], v[124:127]
	v_mfma_f32_16x16x32_bf16 v[120:123], v[72:75], v[168:171], v[120:123]
	v_mfma_f32_16x16x32_bf16 v[108:111], v[64:67], v[176:179], v[108:111]
	v_mfma_f32_16x16x32_bf16 v[104:107], v[72:75], v[176:179], v[104:107]
	v_mfma_f32_16x16x32_bf16 v[92:95], v[64:67], v[184:187], v[92:95]
	v_mfma_f32_16x16x32_bf16 v[88:91], v[72:75], v[184:187], v[88:91]
	v_mfma_f32_16x16x32_bf16 v[140:143], v[68:71], v[164:167], v[140:143]
	v_mfma_f32_16x16x32_bf16 v[136:139], v[76:79], v[164:167], v[136:139]
	v_mfma_f32_16x16x32_bf16 v[124:127], v[68:71], v[172:175], v[124:127]
	v_mfma_f32_16x16x32_bf16 v[120:123], v[76:79], v[172:175], v[120:123]
	v_mfma_f32_16x16x32_bf16 v[108:111], v[68:71], v[180:183], v[108:111]
	v_mfma_f32_16x16x32_bf16 v[104:107], v[76:79], v[180:183], v[104:107]
	v_mfma_f32_16x16x32_bf16 v[92:95], v[68:71], v[188:191], v[92:95]
	v_mfma_f32_16x16x32_bf16 v[88:91], v[76:79], v[188:191], v[88:91]
	s_setprio 0
	s_setprio 1
	v_mfma_f32_16x16x32_bf16 v[132:135], v[144:147], v[160:163], v[132:135]
	v_mfma_f32_16x16x32_bf16 v[128:131], v[152:155], v[160:163], v[128:131]
	v_mfma_f32_16x16x32_bf16 v[116:119], v[144:147], v[168:171], v[116:119]
	v_mfma_f32_16x16x32_bf16 v[112:115], v[152:155], v[168:171], v[112:115]
	v_mfma_f32_16x16x32_bf16 v[100:103], v[144:147], v[176:179], v[100:103]
	v_mfma_f32_16x16x32_bf16 v[96:99], v[152:155], v[176:179], v[96:99]
	v_mfma_f32_16x16x32_bf16 v[84:87], v[144:147], v[184:187], v[84:87]
	v_mfma_f32_16x16x32_bf16 v[80:83], v[152:155], v[184:187], v[80:83]
	v_mfma_f32_16x16x32_bf16 v[132:135], v[148:151], v[164:167], v[132:135]
	v_mfma_f32_16x16x32_bf16 v[128:131], v[156:159], v[164:167], v[128:131]
	v_mfma_f32_16x16x32_bf16 v[116:119], v[148:151], v[172:175], v[116:119]
	v_mfma_f32_16x16x32_bf16 v[112:115], v[156:159], v[172:175], v[112:115]
	v_mfma_f32_16x16x32_bf16 v[100:103], v[148:151], v[180:183], v[100:103]
	v_mfma_f32_16x16x32_bf16 v[96:99], v[156:159], v[180:183], v[96:99]
	v_mfma_f32_16x16x32_bf16 v[84:87], v[148:151], v[188:191], v[84:87]
	v_mfma_f32_16x16x32_bf16 v[80:83], v[156:159], v[188:191], v[80:83]
	s_setprio 0
	s_barrier
	s_add_i32 s19, s86, s63
	v_lshl_add_u64 v[192:193], s[84:85], 0, v[208:209]
	s_mov_b32 m0, s19
	ds_read_b128 v[160:163], v250 offset:16384
	ds_read_b128 v[164:167], v250 offset:17408
	ds_read_b128 v[168:171], v250 offset:18432
	ds_read_b128 v[172:175], v250 offset:19456
	ds_read_b128 v[176:179], v250 offset:20480
	ds_read_b128 v[180:183], v250 offset:21504
	ds_read_b128 v[184:187], v250 offset:22528
	ds_read_b128 v[188:191], v250 offset:23552
	global_load_lds_dwordx4 v[192:193], off
	s_add_i32 m0, s19, 0x2000
	v_lshl_add_u64 v[194:195], s[84:85], 0, v[222:223]
	s_add_u32 s84, s84, s2
	s_addc_u32 s85, s85, 0
	s_add_i32 s18, s18, s63
	global_load_lds_dwordx4 v[194:195], off
	v_lshl_add_u64 v[196:197], s[84:85], 0, v[208:209]
	s_mov_b32 m0, s18
	v_lshl_add_u64 v[198:199], s[84:85], 0, v[222:223]
	global_load_lds_dwordx4 v[196:197], off
	s_add_i32 m0, s18, 0x2000
	v_lshl_add_u64 v[200:201], s[58:59], 0, v[218:219]
	global_load_lds_dwordx4 v[198:199], off
	s_mov_b32 m0, s64
	v_lshl_add_u64 v[202:203], s[58:59], 0, v[220:221]
	global_load_lds_dwordx4 v[200:201], off
	s_mov_b32 m0, s65
	s_nop 0
	global_load_lds_dwordx4 v[202:203], off
	s_waitcnt vmcnt(8)
	s_waitcnt lgkmcnt(0)
	s_setprio 1
	s_barrier
; #define PG8_STAGE(bufoff, gbase, voff) do { _Pragma("unroll") for (int _i = 0; _i < 2; ++_i) \
;         __builtin_amdgcn_global_load_lds((const unsigned*)((const char*)(gbase) + (voff)[_i]), (PG8_LAS unsigned*)(lds + (bufoff) + ldsw + _i * 8192), 16, 0, 0); } while (0)
; #define PG8_LDA(dst, b, h) do { _Pragma("unroll") for (int m = 0; m < 4; ++m) _Pragma("unroll") for (int k = 0; k < 2; ++k) dst[m][k] = *(const PG8_LAS bf16x8*)(lds + PG8_SA(b, h) + aoff + m * 2048 + k * 1024); } while (0)
; #define PG8_LDB(dst, b, h) do { _Pragma("unroll") for (int n = 0; n < 2; ++n) _Pragma("unroll") for (int k = 0; k < 2; ++k) dst[n][k] = *(const PG8_LAS bf16x8*)(lds + PG8_SB(b, h) + boff + n * 2048 + k * 1024); } while (0)
; #define PG8_MMA(ai, bj, At, Bt) do { __builtin_amdgcn_s_setprio(1); _Pragma("unroll") for (int m = 0; m < 4; ++m) _Pragma("unroll") for (int n = 0; n < 2; ++n) _Pragma("unroll") for (int k = 0; k < 2; ++k) \
;         acc[ai][bj][m][n] = __builtin_amdgcn_mfma_f32_16x16x32_bf16(Bt[n][k], At[m][k], acc[ai][bj][m][n], 0, 0, 0); __builtin_amdgcn_s_setprio(0); } while (0)
; #define PG8_WAIT_V(n) asm volatile("s_waitcnt vmcnt(" #n ")" ::: "memory")
; #define PG8_WAIT_L(n) asm volatile("s_waitcnt lgkmcnt(" #n ")" ::: "memory")
; #define PG8_BAR __builtin_amdgcn_s_barrier()
; #define PG8_SCHED __builtin_amdgcn_sched_barrier(0)
; template <class Epi, class Sched, bool ALIGN_EPI = false, bool SP2 = false>
; __device__ __forceinline__ void gemm_phase(PG8_LAS unsigned char* lds, const Gemm g, const Sched& S, const Epi& E) {
;     ...
;             PG8_LDA(At, 0, 1); PG8_STAGE(PG8_SB(0, 0), b2, voffB); PG8_STAGE(PG8_SB(0, 1), b2 + hstep, voffB); PG8_STAGE(PG8_SA(0, 0), a2, voffA);
;             PG8_WAIT_V(8); PG8_WAIT_L(0); PG8_BAR; PG8_MMA(1, 0, At, B0); PG8_MMA(1, 1, At, B1); PG8_BAR; PG8_SCHED;
;             PG8_LDB(B0, 1, 0); PG8_LDB(B1, 1, 1); PG8_SCHED; PG8_LDA(At, 1, 0); PG8_STAGE(PG8_SA(0, 1), a2 + hstep, voffA);
;             PG8_WAIT_V(8); PG8_WAIT_L(0); PG8_BAR; PG8_MMA(0, 0, At, B0); PG8_MMA(0, 1, At, B1); PG8_BAR; PG8_SCHED;
	v_mfma_f32_16x16x32_bf16 v[60:63], v[64:67], v[160:163], v[60:63]
	v_mfma_f32_16x16x32_bf16 v[56:59], v[72:75], v[160:163], v[56:59]
	v_mfma_f32_16x16x32_bf16 v[44:47], v[64:67], v[168:171], v[44:47]
	v_mfma_f32_16x16x32_bf16 v[40:43], v[72:75], v[168:171], v[40:43]
	v_mfma_f32_16x16x32_bf16 v[28:31], v[64:67], v[176:179], v[28:31]
	v_mfma_f32_16x16x32_bf16 v[24:27], v[72:75], v[176:179], v[24:27]
	v_mfma_f32_16x16x32_bf16 v[12:15], v[64:67], v[184:187], v[12:15]
	v_mfma_f32_16x16x32_bf16 v[8:11], v[72:75], v[184:187], v[8:11]
	v_mfma_f32_16x16x32_bf16 v[60:63], v[68:71], v[164:167], v[60:63]
	v_mfma_f32_16x16x32_bf16 v[56:59], v[76:79], v[164:167], v[56:59]
	v_mfma_f32_16x16x32_bf16 v[44:47], v[68:71], v[172:175], v[44:47]
	v_mfma_f32_16x16x32_bf16 v[40:43], v[76:79], v[172:175], v[40:43]
	v_mfma_f32_16x16x32_bf16 v[28:31], v[68:71], v[180:183], v[28:31]
	v_mfma_f32_16x16x32_bf16 v[24:27], v[76:79], v[180:183], v[24:27]
	v_mfma_f32_16x16x32_bf16 v[12:15], v[68:71], v[188:191], v[12:15]
	v_mfma_f32_16x16x32_bf16 v[8:11], v[76:79], v[188:191], v[8:11]
	s_setprio 0
	s_setprio 1
	v_mfma_f32_16x16x32_bf16 v[52:55], v[144:147], v[160:163], v[52:55]
	v_mfma_f32_16x16x32_bf16 v[48:51], v[152:155], v[160:163], v[48:51]
	v_mfma_f32_16x16x32_bf16 v[36:39], v[144:147], v[168:171], v[36:39]
	v_mfma_f32_16x16x32_bf16 v[32:35], v[152:155], v[168:171], v[32:35]
	v_mfma_f32_16x16x32_bf16 v[20:23], v[144:147], v[176:179], v[20:23]
	v_mfma_f32_16x16x32_bf16 v[16:19], v[152:155], v[176:179], v[16:19]
	v_mfma_f32_16x16x32_bf16 v[4:7], v[144:147], v[184:187], v[4:7]
	v_mfma_f32_16x16x32_bf16 v[0:3], v[152:155], v[184:187], v[0:3]
	v_mfma_f32_16x16x32_bf16 v[52:55], v[148:151], v[164:167], v[52:55]
	v_mfma_f32_16x16x32_bf16 v[48:51], v[156:159], v[164:167], v[48:51]
	v_mfma_f32_16x16x32_bf16 v[36:39], v[148:151], v[172:175], v[36:39]
	v_mfma_f32_16x16x32_bf16 v[32:35], v[156:159], v[172:175], v[32:35]
	v_mfma_f32_16x16x32_bf16 v[20:23], v[148:151], v[180:183], v[20:23]
	v_mfma_f32_16x16x32_bf16 v[16:19], v[156:159], v[180:183], v[16:19]
	v_mfma_f32_16x16x32_bf16 v[4:7], v[148:151], v[188:191], v[4:7]
	v_mfma_f32_16x16x32_bf16 v[0:3], v[156:159], v[188:191], v[0:3]
	s_setprio 0
	s_barrier
	s_add_i32 s18, 0, 0x18000
	s_add_i32 s19, 0, 0x1c000
	v_add_u32_e32 v76, s18, v248
	v_add_u32_e32 v156, s19, v248
	ds_read_b128 v[64:67], v76
	ds_read_b128 v[68:71], v76 offset:1024
	ds_read_b128 v[72:75], v76 offset:2048
	ds_read_b128 v[76:79], v76 offset:3072
	ds_read_b128 v[144:147], v156
	ds_read_b128 v[148:151], v156 offset:1024
	ds_read_b128 v[152:155], v156 offset:2048
	ds_read_b128 v[156:159], v156 offset:3072
	s_add_u32 s58, s58, s2
	s_addc_u32 s59, s59, 0
	s_mov_b32 m0, s66
	v_lshl_add_u64 v[204:205], s[58:59], 0, v[218:219]
	ds_read_b128 v[160:163], v250 offset:32768
	ds_read_b128 v[164:167], v250 offset:33792
	ds_read_b128 v[168:171], v250 offset:34816
	ds_read_b128 v[172:175], v250 offset:35840
	ds_read_b128 v[176:179], v250 offset:36864
	ds_read_b128 v[180:183], v250 offset:37888
	ds_read_b128 v[184:187], v250 offset:38912
	ds_read_b128 v[188:191], v250 offset:39936
	global_load_lds_dwordx4 v[204:205], off
	v_lshl_add_u64 v[204:205], s[58:59], 0, v[220:221]
	s_mov_b32 m0, s67
	s_nop 0
	global_load_lds_dwordx4 v[204:205], off
	s_waitcnt vmcnt(8)
	s_waitcnt lgkmcnt(0)
	s_setprio 1
	s_barrier
	v_mfma_f32_16x16x32_bf16 v[140:143], v[64:67], v[160:163], v[140:143]
	v_mfma_f32_16x16x32_bf16 v[136:139], v[72:75], v[160:163], v[136:139]
	v_mfma_f32_16x16x32_bf16 v[124:127], v[64:67], v[168:171], v[124:127]
	v_mfma_f32_16x16x32_bf16 v[120:123], v[72:75], v[168:171], v[120:123]
	v_mfma_f32_16x16x32_bf16 v[108:111], v[64:67], v[176:179], v[108:111]
	v_mfma_f32_16x16x32_bf16 v[104:107], v[72:75], v[176:179], v[104:107]
	v_mfma_f32_16x16x32_bf16 v[92:95], v[64:67], v[184:187], v[92:95]
	v_mfma_f32_16x16x32_bf16 v[88:91], v[72:75], v[184:187], v[88:91]
	v_mfma_f32_16x16x32_bf16 v[140:143], v[68:71], v[164:167], v[140:143]
	v_mfma_f32_16x16x32_bf16 v[136:139], v[76:79], v[164:167], v[136:139]
	v_mfma_f32_16x16x32_bf16 v[124:127], v[68:71], v[172:175], v[124:127]
	v_mfma_f32_16x16x32_bf16 v[120:123], v[76:79], v[172:175], v[120:123]
	v_mfma_f32_16x16x32_bf16 v[108:111], v[68:71], v[180:183], v[108:111]
	v_mfma_f32_16x16x32_bf16 v[104:107], v[76:79], v[180:183], v[104:107]
	v_mfma_f32_16x16x32_bf16 v[92:95], v[68:71], v[188:191], v[92:95]
	v_mfma_f32_16x16x32_bf16 v[88:91], v[76:79], v[188:191], v[88:91]
	s_setprio 0
	s_setprio 1
	v_mfma_f32_16x16x32_bf16 v[132:135], v[144:147], v[160:163], v[132:135]
	v_mfma_f32_16x16x32_bf16 v[128:131], v[152:155], v[160:163], v[128:131]
	v_mfma_f32_16x16x32_bf16 v[116:119], v[144:147], v[168:171], v[116:119]
	v_mfma_f32_16x16x32_bf16 v[112:115], v[152:155], v[168:171], v[112:115]
	v_mfma_f32_16x16x32_bf16 v[100:103], v[144:147], v[176:179], v[100:103]
	v_mfma_f32_16x16x32_bf16 v[96:99], v[152:155], v[176:179], v[96:99]
	v_mfma_f32_16x16x32_bf16 v[84:87], v[144:147], v[184:187], v[84:87]
	v_mfma_f32_16x16x32_bf16 v[80:83], v[152:155], v[184:187], v[80:83]
	v_mfma_f32_16x16x32_bf16 v[132:135], v[148:151], v[164:167], v[132:135]
	v_mfma_f32_16x16x32_bf16 v[128:131], v[156:159], v[164:167], v[128:131]
	v_mfma_f32_16x16x32_bf16 v[116:119], v[148:151], v[172:175], v[116:119]
	v_mfma_f32_16x16x32_bf16 v[112:115], v[156:159], v[172:175], v[112:115]
	v_mfma_f32_16x16x32_bf16 v[100:103], v[148:151], v[180:183], v[100:103]
	v_mfma_f32_16x16x32_bf16 v[96:99], v[156:159], v[180:183], v[96:99]
	v_mfma_f32_16x16x32_bf16 v[84:87], v[148:151], v[188:191], v[84:87]
	v_mfma_f32_16x16x32_bf16 v[80:83], v[156:159], v[188:191], v[80:83]
	s_setprio 0
	s_barrier
; #define PG8_STAGE(bufoff, gbase, voff) do { _Pragma("unroll") for (int _i = 0; _i < 2; ++_i) \
;         __builtin_amdgcn_global_load_lds((const unsigned*)((const char*)(gbase) + (voff)[_i]), (PG8_LAS unsigned*)(lds + (bufoff) + ldsw + _i * 8192), 16, 0, 0); } while (0)
; #define PG8_LDA(dst, b, h) do { _Pragma("unroll") for (int m = 0; m < 4; ++m) _Pragma("unroll") for (int k = 0; k < 2; ++k) dst[m][k] = *(const PG8_LAS bf16x8*)(lds + PG8_SA(b, h) + aoff + m * 2048 + k * 1024); } while (0)
; #define PG8_LDB(dst, b, h) do { _Pragma("unroll") for (int n = 0; n < 2; ++n) _Pragma("unroll") for (int k = 0; k < 2; ++k) dst[n][k] = *(const PG8_LAS bf16x8*)(lds + PG8_SB(b, h) + boff + n * 2048 + k * 1024); } while (0)
; #define PG8_MMA(ai, bj, At, Bt) do { __builtin_amdgcn_s_setprio(1); _Pragma("unroll") for (int m = 0; m < 4; ++m) _Pragma("unroll") for (int n = 0; n < 2; ++n) _Pragma("unroll") for (int k = 0; k < 2; ++k) \
;         acc[ai][bj][m][n] = __builtin_amdgcn_mfma_f32_16x16x32_bf16(Bt[n][k], At[m][k], acc[ai][bj][m][n], 0, 0, 0); __builtin_amdgcn_s_setprio(0); } while (0)
; #define PG8_WAIT_V(n) asm volatile("s_waitcnt vmcnt(" #n ")" ::: "memory")
; #define PG8_WAIT_L(n) asm volatile("s_waitcnt lgkmcnt(" #n ")" ::: "memory")
; #define PG8_BAR __builtin_amdgcn_s_barrier()
; #define PG8_SCHED __builtin_amdgcn_sched_barrier(0)
; template <class Epi, class Sched, bool ALIGN_EPI = false, bool SP2 = false>
; __device__ __forceinline__ void gemm_phase(PG8_LAS unsigned char* lds, const Gemm g, const Sched& S, const Epi& E) {
;     ...
;             PG8_LDB(B0, 1, 0); PG8_LDB(B1, 1, 1); PG8_SCHED; PG8_LDA(At, 1, 0); PG8_STAGE(PG8_SA(0, 1), a2 + hstep, voffA);
;             PG8_WAIT_V(8); PG8_WAIT_L(0); PG8_BAR; PG8_MMA(0, 0, At, B0); PG8_MMA(0, 1, At, B1); PG8_BAR; PG8_SCHED;
;             PG8_LDA(At, 1, 1); PG8_STAGE(PG8_SB(1, 0), b3, voffB); PG8_STAGE(PG8_SB(1, 1), b3 + hstep, voffB); PG8_STAGE(PG8_SA(1, 0), a3, voffA);
;             PG8_WAIT_V(8); PG8_WAIT_L(0); PG8_BAR; PG8_MMA(1, 0, At, B0); PG8_MMA(1, 1, At, B1); PG8_BAR; PG8_SCHED;
	s_add_i32 s18, s18, s63
	v_lshl_add_u64 v[192:193], v[192:193], 0, s[24:25]
	s_mov_b32 m0, s18
	ds_read_b128 v[160:163], v250 offset:49152
	ds_read_b128 v[164:167], v250 offset:50176
	ds_read_b128 v[168:171], v250 offset:51200
	ds_read_b128 v[172:175], v250 offset:52224
	ds_read_b128 v[176:179], v250 offset:53248
	ds_read_b128 v[180:183], v250 offset:54272
	ds_read_b128 v[184:187], v250 offset:55296
	ds_read_b128 v[188:191], v250 offset:56320
	global_load_lds_dwordx4 v[192:193], off
	v_lshl_add_u64 v[192:193], v[194:195], 0, s[24:25]
	s_add_i32 m0, s18, 0x2000
	s_add_i32 s18, s19, s63
	global_load_lds_dwordx4 v[192:193], off
	v_lshl_add_u64 v[192:193], v[196:197], 0, s[24:25]
	s_mov_b32 m0, s18
	s_nop 0
	global_load_lds_dwordx4 v[192:193], off
	v_lshl_add_u64 v[192:193], v[198:199], 0, s[24:25]
	s_add_i32 m0, s18, 0x2000
	s_nop 0
	global_load_lds_dwordx4 v[192:193], off
	v_lshl_add_u64 v[192:193], v[200:201], 0, s[24:25]
	s_mov_b32 m0, s68
	s_nop 0
	global_load_lds_dwordx4 v[192:193], off
	v_lshl_add_u64 v[192:193], v[202:203], 0, s[24:25]
	s_mov_b32 m0, s69
	s_nop 0
	global_load_lds_dwordx4 v[192:193], off
	s_waitcnt vmcnt(8)
	s_waitcnt lgkmcnt(0)
	s_setprio 1
	s_barrier
	v_mfma_f32_16x16x32_bf16 v[60:63], v[64:67], v[160:163], v[60:63]
	v_mfma_f32_16x16x32_bf16 v[56:59], v[72:75], v[160:163], v[56:59]
	v_mfma_f32_16x16x32_bf16 v[44:47], v[64:67], v[168:171], v[44:47]
	v_mfma_f32_16x16x32_bf16 v[40:43], v[72:75], v[168:171], v[40:43]
	v_mfma_f32_16x16x32_bf16 v[28:31], v[64:67], v[176:179], v[28:31]
	v_mfma_f32_16x16x32_bf16 v[24:27], v[72:75], v[176:179], v[24:27]
	v_mfma_f32_16x16x32_bf16 v[12:15], v[64:67], v[184:187], v[12:15]
	v_mfma_f32_16x16x32_bf16 v[8:11], v[72:75], v[184:187], v[8:11]
	v_mfma_f32_16x16x32_bf16 v[60:63], v[68:71], v[164:167], v[60:63]
	v_mfma_f32_16x16x32_bf16 v[56:59], v[76:79], v[164:167], v[56:59]
	v_mfma_f32_16x16x32_bf16 v[44:47], v[68:71], v[172:175], v[44:47]
	v_mfma_f32_16x16x32_bf16 v[40:43], v[76:79], v[172:175], v[40:43]
	v_mfma_f32_16x16x32_bf16 v[28:31], v[68:71], v[180:183], v[28:31]
	v_mfma_f32_16x16x32_bf16 v[24:27], v[76:79], v[180:183], v[24:27]
	v_mfma_f32_16x16x32_bf16 v[12:15], v[68:71], v[188:191], v[12:15]
	v_mfma_f32_16x16x32_bf16 v[8:11], v[76:79], v[188:191], v[8:11]
	s_setprio 0
	s_setprio 1
	v_mfma_f32_16x16x32_bf16 v[52:55], v[144:147], v[160:163], v[52:55]
	v_mfma_f32_16x16x32_bf16 v[48:51], v[152:155], v[160:163], v[48:51]
	v_mfma_f32_16x16x32_bf16 v[36:39], v[144:147], v[168:171], v[36:39]
	v_mfma_f32_16x16x32_bf16 v[32:35], v[152:155], v[168:171], v[32:35]
	v_mfma_f32_16x16x32_bf16 v[20:23], v[144:147], v[176:179], v[20:23]
	v_mfma_f32_16x16x32_bf16 v[16:19], v[152:155], v[176:179], v[16:19]
	v_mfma_f32_16x16x32_bf16 v[4:7], v[144:147], v[184:187], v[4:7]
	v_mfma_f32_16x16x32_bf16 v[0:3], v[152:155], v[184:187], v[0:3]
	v_mfma_f32_16x16x32_bf16 v[52:55], v[148:151], v[164:167], v[52:55]
	v_mfma_f32_16x16x32_bf16 v[48:51], v[156:159], v[164:167], v[48:51]
	v_mfma_f32_16x16x32_bf16 v[36:39], v[148:151], v[172:175], v[36:39]
	v_mfma_f32_16x16x32_bf16 v[32:35], v[156:159], v[172:175], v[32:35]
	v_mfma_f32_16x16x32_bf16 v[20:23], v[148:151], v[180:183], v[20:23]
	v_mfma_f32_16x16x32_bf16 v[16:19], v[156:159], v[180:183], v[16:19]
	v_mfma_f32_16x16x32_bf16 v[4:7], v[148:151], v[188:191], v[4:7]
	v_mfma_f32_16x16x32_bf16 v[0:3], v[156:159], v[188:191], v[0:3]
	s_setprio 0
	s_barrier
	s_add_u32 s56, s56, 0x100
	s_addc_u32 s57, s57, 0
	s_add_u32 s38, s38, 0x100
	s_addc_u32 s78, s78, 0
	s_cmp_ge_u32 s79, s71
	s_mov_b32 s58, s79
	s_cbranch_scc0 .LBB0_62
	s_and_b64 vcc, exec, s[48:49]
	s_cbranch_vccz .LBB0_65
	s_barrier

; #define PG8_STAGE(bufoff, gbase, voff) do { _Pragma("unroll") for (int _i = 0; _i < 2; ++_i) \
;         __builtin_amdgcn_global_load_lds((const unsigned*)((const char*)(gbase) + (voff)[_i]), (PG8_LAS unsigned*)(lds + (bufoff) + ldsw + _i * 8192), 16, 0, 0); } while (0)
; #define PG8_LDA(dst, b, h) do { _Pragma("unroll") for (int m = 0; m < 4; ++m) _Pragma("unroll") for (int k = 0; k < 2; ++k) dst[m][k] = *(const PG8_LAS bf16x8*)(lds + PG8_SA(b, h) + aoff + m * 2048 + k * 1024); } while (0)
; #define PG8_LDB(dst, b, h) do { _Pragma("unroll") for (int n = 0; n < 2; ++n) _Pragma("unroll") for (int k = 0; k < 2; ++k) dst[n][k] = *(const PG8_LAS bf16x8*)(lds + PG8_SB(b, h) + boff + n * 2048 + k * 1024); } while (0)
; #define PG8_WAIT_V(n) asm volatile("s_waitcnt vmcnt(" #n ")" ::: "memory")
; #define PG8_WAIT_L(n) asm volatile("s_waitcnt lgkmcnt(" #n ")" ::: "memory")
; #define PG8_BAR __builtin_amdgcn_s_barrier()
; #define PG8_SCHED __builtin_amdgcn_sched_barrier(0)
; template <class Epi, class Sched, bool ALIGN_EPI = false, bool SP2 = false>
; __device__ __forceinline__ void gemm_phase(PG8_LAS unsigned char* lds, const Gemm g, const Sched& S, const Epi& E) {
;     ...
;         const char* nA = has_next ? (const char*)g.A + S.a_byte(nxt, K) : cA; const char* nB = has_next ? (const char*)g.Bt + (size_t)nxt.pn * tstep : cB;
;         for (int t = 0; t < nt; t += 2) {
;             const bool last = (t == nt - 2);
;             const char* a1 = cA + (size_t)(t + 1) * kstep;
;             const char* a2 = last ? nA : cA + (size_t)(t + 2) * kstep; const char* b2 = last ? nB : cB + (size_t)(t + 2) * kstep;
;             const char* a3 = a2 + kstep; const char* b3 = b2 + kstep;
;             if (last && has_next) S.a_ready(nxt);
;             if constexpr (SP2) {
;             PG8_LDB(B0, 0, 0); PG8_LDB(B1, 0, 1); PG8_SCHED; PG8_LDA(At, 0, 0); PG8_STAGE(PG8_SA(1, 1), a1 + hstep, voffA);
;             PG8_WAIT_V(8); PG8_WAIT_L(0); PG8_BAR; PG8_MMA(0, 0, At, B0); PG8_MMA(0, 1, At, B1); PG8_BAR; PG8_SCHED;
;             PG8_LDA(At, 0, 1); PG8_STAGE(PG8_SB(0, 0), b2, voffB); PG8_STAGE(PG8_SB(0, 1), b2 + hstep, voffB); PG8_STAGE(PG8_SA(0, 0), a2, voffA);
;             PG8_WAIT_V(8); PG8_WAIT_L(0); PG8_BAR; PG8_MMA(1, 0, At, B0); PG8_MMA(1, 1, At, B1); PG8_BAR; PG8_SCHED;
.LBB0_138:
	s_add_u32 s18, s50, 0xfffc0080
	s_addc_u32 s19, s51, -1
	s_add_i32 s69, 0, 0x10000
	s_cmp_eq_u32 s68, 12
	s_cselect_b32 s55, s41, s19
	s_cselect_b32 s54, s49, s18
	s_cselect_b32 s53, s21, s67
	s_cselect_b32 s52, s65, s66
	s_add_i32 s18, 0, 0x14000
	v_add_u32_e32 v140, s69, v171
	v_add_u32_e32 v166, s18, v171
	ds_read_b128 v[128:131], v140
	ds_read_b128 v[132:135], v140 offset:1024
	ds_read_b128 v[136:139], v140 offset:2048
	ds_read_b128 v[140:143], v140 offset:3072
	ds_read_b128 v[144:147], v166
	ds_read_b128 v[158:161], v166 offset:1024
	ds_read_b128 v[162:165], v166 offset:2048
	ds_read_b128 v[166:169], v166 offset:3072
	v_lshl_add_u64 v[206:207], s[50:51], 0, v[154:155]
	s_add_i32 m0, s57, 0xc000
	ds_read_b128 v[174:177], v173
	ds_read_b128 v[178:181], v173 offset:1024
	ds_read_b128 v[182:185], v173 offset:2048
	ds_read_b128 v[186:189], v173 offset:3072
	ds_read_b128 v[190:193], v173 offset:4096
	ds_read_b128 v[194:197], v173 offset:5120
	ds_read_b128 v[198:201], v173 offset:6144
	ds_read_b128 v[202:205], v173 offset:7168
	global_load_lds_dwordx4 v[206:207], off
	v_lshl_add_u64 v[206:207], s[50:51], 0, v[156:157]
	s_add_i32 m0, s57, 0xe000
	s_nop 0
	global_load_lds_dwordx4 v[206:207], off
	s_waitcnt vmcnt(8)
	s_waitcnt lgkmcnt(0)
	s_setprio 1
	s_barrier
	v_mfma_f32_16x16x32_bf16 v[124:127], v[128:131], v[174:177], v[124:127]
	v_mfma_f32_16x16x32_bf16 v[120:123], v[136:139], v[174:177], v[120:123]
	v_mfma_f32_16x16x32_bf16 v[116:119], v[128:131], v[182:185], v[116:119]
	v_mfma_f32_16x16x32_bf16 v[112:115], v[136:139], v[182:185], v[112:115]
	v_mfma_f32_16x16x32_bf16 v[96:99], v[128:131], v[190:193], v[96:99]
	v_mfma_f32_16x16x32_bf16 v[92:95], v[136:139], v[190:193], v[92:95]
	v_mfma_f32_16x16x32_bf16 v[84:87], v[128:131], v[198:201], v[84:87]
	v_mfma_f32_16x16x32_bf16 v[80:83], v[136:139], v[198:201], v[80:83]
	v_mfma_f32_16x16x32_bf16 v[124:127], v[132:135], v[178:181], v[124:127]
	v_mfma_f32_16x16x32_bf16 v[120:123], v[140:143], v[178:181], v[120:123]
	v_mfma_f32_16x16x32_bf16 v[116:119], v[132:135], v[186:189], v[116:119]
	v_mfma_f32_16x16x32_bf16 v[112:115], v[140:143], v[186:189], v[112:115]
	v_mfma_f32_16x16x32_bf16 v[96:99], v[132:135], v[194:197], v[96:99]
	v_mfma_f32_16x16x32_bf16 v[92:95], v[140:143], v[194:197], v[92:95]
	v_mfma_f32_16x16x32_bf16 v[84:87], v[132:135], v[202:205], v[84:87]
	v_mfma_f32_16x16x32_bf16 v[80:83], v[140:143], v[202:205], v[80:83]
	s_setprio 0
	s_setprio 1
	v_mfma_f32_16x16x32_bf16 v[108:111], v[144:147], v[174:177], v[108:111]
	v_mfma_f32_16x16x32_bf16 v[104:107], v[162:165], v[174:177], v[104:107]
	v_mfma_f32_16x16x32_bf16 v[100:103], v[144:147], v[182:185], v[100:103]
	v_mfma_f32_16x16x32_bf16 v[88:91], v[162:165], v[182:185], v[88:91]
	v_mfma_f32_16x16x32_bf16 v[76:79], v[144:147], v[190:193], v[76:79]
	v_mfma_f32_16x16x32_bf16 v[72:75], v[162:165], v[190:193], v[72:75]
	v_mfma_f32_16x16x32_bf16 v[68:71], v[144:147], v[198:201], v[68:71]
	v_mfma_f32_16x16x32_bf16 v[64:67], v[162:165], v[198:201], v[64:67]
	v_mfma_f32_16x16x32_bf16 v[108:111], v[158:161], v[178:181], v[108:111]
	v_mfma_f32_16x16x32_bf16 v[104:107], v[166:169], v[178:181], v[104:107]
	v_mfma_f32_16x16x32_bf16 v[100:103], v[158:161], v[186:189], v[100:103]
	v_mfma_f32_16x16x32_bf16 v[88:91], v[166:169], v[186:189], v[88:91]
	v_mfma_f32_16x16x32_bf16 v[76:79], v[158:161], v[194:197], v[76:79]
	v_mfma_f32_16x16x32_bf16 v[72:75], v[166:169], v[194:197], v[72:75]
	v_mfma_f32_16x16x32_bf16 v[68:71], v[158:161], v[202:205], v[68:71]
	v_mfma_f32_16x16x32_bf16 v[64:67], v[166:169], v[202:205], v[64:67]
	s_setprio 0
	s_barrier
	s_add_i32 s19, s69, s56
	v_lshl_add_u64 v[206:207], s[52:53], 0, v[208:209]
	s_mov_b32 m0, s19
	ds_read_b128 v[174:177], v173 offset:16384
	ds_read_b128 v[178:181], v173 offset:17408
	ds_read_b128 v[182:185], v173 offset:18432
	ds_read_b128 v[186:189], v173 offset:19456
	ds_read_b128 v[190:193], v173 offset:20480
	ds_read_b128 v[194:197], v173 offset:21504
	ds_read_b128 v[198:201], v173 offset:22528
	ds_read_b128 v[202:205], v173 offset:23552
	global_load_lds_dwordx4 v[206:207], off
	s_add_i32 m0, s19, 0x2000
	s_add_u32 s70, s52, 0x40000
	v_lshl_add_u64 v[212:213], s[52:53], 0, v[152:153]
	s_addc_u32 s71, s53, 0
	s_add_i32 s18, s18, s56
	global_load_lds_dwordx4 v[212:213], off
	v_lshl_add_u64 v[214:215], s[70:71], 0, v[208:209]
	s_mov_b32 m0, s18
	v_lshl_add_u64 v[218:219], s[54:55], 0, v[150:151]
	global_load_lds_dwordx4 v[214:215], off
	v_lshl_add_u64 v[214:215], s[70:71], 0, v[152:153]
	s_add_i32 m0, s18, 0x2000
	s_nop 0
	global_load_lds_dwordx4 v[214:215], off
	v_lshl_add_u64 v[214:215], s[54:55], 0, v[148:149]
	s_mov_b32 m0, s57
	s_nop 0
	global_load_lds_dwordx4 v[214:215], off
	s_mov_b32 m0, s58
	s_nop 0
	global_load_lds_dwordx4 v[218:219], off
	s_waitcnt vmcnt(8)
	s_waitcnt lgkmcnt(0)
	s_setprio 1
	s_barrier
; #define PG8_STAGE(bufoff, gbase, voff) do { _Pragma("unroll") for (int _i = 0; _i < 2; ++_i) \
;         __builtin_amdgcn_global_load_lds((const unsigned*)((const char*)(gbase) + (voff)[_i]), (PG8_LAS unsigned*)(lds + (bufoff) + ldsw + _i * 8192), 16, 0, 0); } while (0)
; #define PG8_LDA(dst, b, h) do { _Pragma("unroll") for (int m = 0; m < 4; ++m) _Pragma("unroll") for (int k = 0; k < 2; ++k) dst[m][k] = *(const PG8_LAS bf16x8*)(lds + PG8_SA(b, h) + aoff + m * 2048 + k * 1024); } while (0)
; #define PG8_LDB(dst, b, h) do { _Pragma("unroll") for (int n = 0; n < 2; ++n) _Pragma("unroll") for (int k = 0; k < 2; ++k) dst[n][k] = *(const PG8_LAS bf16x8*)(lds + PG8_SB(b, h) + boff + n * 2048 + k * 1024); } while (0)
; #define PG8_MMA(ai, bj, At, Bt) do { __builtin_amdgcn_s_setprio(1); _Pragma("unroll") for (int m = 0; m < 4; ++m) _Pragma("unroll") for (int n = 0; n < 2; ++n) _Pragma("unroll") for (int k = 0; k < 2; ++k) \
;         acc[ai][bj][m][n] = __builtin_amdgcn_mfma_f32_16x16x32_bf16(Bt[n][k], At[m][k], acc[ai][bj][m][n], 0, 0, 0); __builtin_amdgcn_s_setprio(0); } while (0)
; #define PG8_WAIT_V(n) asm volatile("s_waitcnt vmcnt(" #n ")" ::: "memory")
; #define PG8_WAIT_L(n) asm volatile("s_waitcnt lgkmcnt(" #n ")" ::: "memory")
; #define PG8_BAR __builtin_amdgcn_s_barrier()
; #define PG8_SCHED __builtin_amdgcn_sched_barrier(0)
; template <class Epi, class Sched, bool ALIGN_EPI = false, bool SP2 = false>
; __device__ __forceinline__ void gemm_phase(PG8_LAS unsigned char* lds, const Gemm g, const Sched& S, const Epi& E) {
;     ...
;             PG8_LDA(At, 0, 1); PG8_STAGE(PG8_SB(0, 0), b2, voffB); PG8_STAGE(PG8_SB(0, 1), b2 + hstep, voffB); PG8_STAGE(PG8_SA(0, 0), a2, voffA);
;             PG8_WAIT_V(8); PG8_WAIT_L(0); PG8_BAR; PG8_MMA(1, 0, At, B0); PG8_MMA(1, 1, At, B1); PG8_BAR; PG8_SCHED;
;             PG8_LDB(B0, 1, 0); PG8_LDB(B1, 1, 1); PG8_SCHED; PG8_LDA(At, 1, 0); PG8_STAGE(PG8_SA(0, 1), a2 + hstep, voffA);
;             PG8_WAIT_V(8); PG8_WAIT_L(0); PG8_BAR; PG8_MMA(0, 0, At, B0); PG8_MMA(0, 1, At, B1); PG8_BAR; PG8_SCHED;
	v_mfma_f32_16x16x32_bf16 v[60:63], v[128:131], v[174:177], v[60:63]
	v_mfma_f32_16x16x32_bf16 v[56:59], v[136:139], v[174:177], v[56:59]
	v_mfma_f32_16x16x32_bf16 v[48:51], v[128:131], v[182:185], v[48:51]
	v_mfma_f32_16x16x32_bf16 v[40:43], v[136:139], v[182:185], v[40:43]
	v_mfma_f32_16x16x32_bf16 v[32:35], v[128:131], v[190:193], v[32:35]
	v_mfma_f32_16x16x32_bf16 v[24:27], v[136:139], v[190:193], v[24:27]
	v_mfma_f32_16x16x32_bf16 v[16:19], v[128:131], v[198:201], v[16:19]
	v_mfma_f32_16x16x32_bf16 v[8:11], v[136:139], v[198:201], v[8:11]
	v_mfma_f32_16x16x32_bf16 v[60:63], v[132:135], v[178:181], v[60:63]
	v_mfma_f32_16x16x32_bf16 v[56:59], v[140:143], v[178:181], v[56:59]
	v_mfma_f32_16x16x32_bf16 v[48:51], v[132:135], v[186:189], v[48:51]
	v_mfma_f32_16x16x32_bf16 v[40:43], v[140:143], v[186:189], v[40:43]
	v_mfma_f32_16x16x32_bf16 v[32:35], v[132:135], v[194:197], v[32:35]
	v_mfma_f32_16x16x32_bf16 v[24:27], v[140:143], v[194:197], v[24:27]
	v_mfma_f32_16x16x32_bf16 v[16:19], v[132:135], v[202:205], v[16:19]
	v_mfma_f32_16x16x32_bf16 v[8:11], v[140:143], v[202:205], v[8:11]
	s_setprio 0
	s_setprio 1
	v_mfma_f32_16x16x32_bf16 v[52:55], v[144:147], v[174:177], v[52:55]
	v_mfma_f32_16x16x32_bf16 v[44:47], v[162:165], v[174:177], v[44:47]
	v_mfma_f32_16x16x32_bf16 v[36:39], v[144:147], v[182:185], v[36:39]
	v_mfma_f32_16x16x32_bf16 v[28:31], v[162:165], v[182:185], v[28:31]
	v_mfma_f32_16x16x32_bf16 v[20:23], v[144:147], v[190:193], v[20:23]
	v_mfma_f32_16x16x32_bf16 v[12:15], v[162:165], v[190:193], v[12:15]
	v_mfma_f32_16x16x32_bf16 v[4:7], v[144:147], v[198:201], v[4:7]
	v_mfma_f32_16x16x32_bf16 v[0:3], v[162:165], v[198:201], v[0:3]
	v_mfma_f32_16x16x32_bf16 v[52:55], v[158:161], v[178:181], v[52:55]
	v_mfma_f32_16x16x32_bf16 v[44:47], v[166:169], v[178:181], v[44:47]
	v_mfma_f32_16x16x32_bf16 v[36:39], v[158:161], v[186:189], v[36:39]
	v_mfma_f32_16x16x32_bf16 v[28:31], v[166:169], v[186:189], v[28:31]
	v_mfma_f32_16x16x32_bf16 v[20:23], v[158:161], v[194:197], v[20:23]
	v_mfma_f32_16x16x32_bf16 v[12:15], v[166:169], v[194:197], v[12:15]
	v_mfma_f32_16x16x32_bf16 v[4:7], v[158:161], v[202:205], v[4:7]
	v_mfma_f32_16x16x32_bf16 v[0:3], v[166:169], v[202:205], v[0:3]
	s_setprio 0
	s_barrier
	s_add_i32 s18, 0, 0x18000
	s_add_i32 s19, 0, 0x1c000
	v_add_u32_e32 v140, s18, v171
	v_add_u32_e32 v166, s19, v171
	ds_read_b128 v[128:131], v140
	ds_read_b128 v[132:135], v140 offset:1024
	ds_read_b128 v[136:139], v140 offset:2048
	ds_read_b128 v[140:143], v140 offset:3072
	ds_read_b128 v[144:147], v166
	ds_read_b128 v[158:161], v166 offset:1024
	ds_read_b128 v[162:165], v166 offset:2048
	ds_read_b128 v[166:169], v166 offset:3072
	s_add_u32 s54, s54, 0x40000
	s_addc_u32 s55, s55, 0
	s_mov_b32 m0, s59
	v_lshl_add_u64 v[220:221], s[54:55], 0, v[148:149]
	ds_read_b128 v[174:177], v173 offset:32768
	ds_read_b128 v[178:181], v173 offset:33792
	ds_read_b128 v[182:185], v173 offset:34816
	ds_read_b128 v[186:189], v173 offset:35840
	ds_read_b128 v[190:193], v173 offset:36864
	ds_read_b128 v[194:197], v173 offset:37888
	ds_read_b128 v[198:201], v173 offset:38912
	ds_read_b128 v[202:205], v173 offset:39936
	global_load_lds_dwordx4 v[220:221], off
	v_lshl_add_u64 v[220:221], s[54:55], 0, v[150:151]
	s_mov_b32 m0, s60
	s_nop 0
	global_load_lds_dwordx4 v[220:221], off
	s_waitcnt vmcnt(8)
	s_waitcnt lgkmcnt(0)
	s_setprio 1
	s_barrier
	v_mfma_f32_16x16x32_bf16 v[124:127], v[128:131], v[174:177], v[124:127]
	v_mfma_f32_16x16x32_bf16 v[120:123], v[136:139], v[174:177], v[120:123]
	v_mfma_f32_16x16x32_bf16 v[116:119], v[128:131], v[182:185], v[116:119]
	v_mfma_f32_16x16x32_bf16 v[112:115], v[136:139], v[182:185], v[112:115]
	v_mfma_f32_16x16x32_bf16 v[96:99], v[128:131], v[190:193], v[96:99]
	v_mfma_f32_16x16x32_bf16 v[92:95], v[136:139], v[190:193], v[92:95]
	v_mfma_f32_16x16x32_bf16 v[84:87], v[128:131], v[198:201], v[84:87]
	v_mfma_f32_16x16x32_bf16 v[80:83], v[136:139], v[198:201], v[80:83]
	v_mfma_f32_16x16x32_bf16 v[124:127], v[132:135], v[178:181], v[124:127]
	v_mfma_f32_16x16x32_bf16 v[120:123], v[140:143], v[178:181], v[120:123]
	v_mfma_f32_16x16x32_bf16 v[116:119], v[132:135], v[186:189], v[116:119]
	v_mfma_f32_16x16x32_bf16 v[112:115], v[140:143], v[186:189], v[112:115]
	v_mfma_f32_16x16x32_bf16 v[96:99], v[132:135], v[194:197], v[96:99]
	v_mfma_f32_16x16x32_bf16 v[92:95], v[140:143], v[194:197], v[92:95]
	v_mfma_f32_16x16x32_bf16 v[84:87], v[132:135], v[202:205], v[84:87]
	v_mfma_f32_16x16x32_bf16 v[80:83], v[140:143], v[202:205], v[80:83]
	s_setprio 0
	s_setprio 1
	v_mfma_f32_16x16x32_bf16 v[108:111], v[144:147], v[174:177], v[108:111]
	v_mfma_f32_16x16x32_bf16 v[104:107], v[162:165], v[174:177], v[104:107]
	v_mfma_f32_16x16x32_bf16 v[100:103], v[144:147], v[182:185], v[100:103]
	v_mfma_f32_16x16x32_bf16 v[88:91], v[162:165], v[182:185], v[88:91]
	v_mfma_f32_16x16x32_bf16 v[76:79], v[144:147], v[190:193], v[76:79]
	v_mfma_f32_16x16x32_bf16 v[72:75], v[162:165], v[190:193], v[72:75]
	v_mfma_f32_16x16x32_bf16 v[68:71], v[144:147], v[198:201], v[68:71]
	v_mfma_f32_16x16x32_bf16 v[64:67], v[162:165], v[198:201], v[64:67]
	v_mfma_f32_16x16x32_bf16 v[108:111], v[158:161], v[178:181], v[108:111]
	v_mfma_f32_16x16x32_bf16 v[104:107], v[166:169], v[178:181], v[104:107]
	v_mfma_f32_16x16x32_bf16 v[100:103], v[158:161], v[186:189], v[100:103]
	v_mfma_f32_16x16x32_bf16 v[88:91], v[166:169], v[186:189], v[88:91]
	v_mfma_f32_16x16x32_bf16 v[76:79], v[158:161], v[194:197], v[76:79]
	v_mfma_f32_16x16x32_bf16 v[72:75], v[166:169], v[194:197], v[72:75]
	v_mfma_f32_16x16x32_bf16 v[68:71], v[158:161], v[202:205], v[68:71]
	v_mfma_f32_16x16x32_bf16 v[64:67], v[166:169], v[202:205], v[64:67]
	s_setprio 0
	s_barrier
; #define PG8_STAGE(bufoff, gbase, voff) do { _Pragma("unroll") for (int _i = 0; _i < 2; ++_i) \
;         __builtin_amdgcn_global_load_lds((const unsigned*)((const char*)(gbase) + (voff)[_i]), (PG8_LAS unsigned*)(lds + (bufoff) + ldsw + _i * 8192), 16, 0, 0); } while (0)
; #define PG8_LDA(dst, b, h) do { _Pragma("unroll") for (int m = 0; m < 4; ++m) _Pragma("unroll") for (int k = 0; k < 2; ++k) dst[m][k] = *(const PG8_LAS bf16x8*)(lds + PG8_SA(b, h) + aoff + m * 2048 + k * 1024); } while (0)
; #define PG8_LDB(dst, b, h) do { _Pragma("unroll") for (int n = 0; n < 2; ++n) _Pragma("unroll") for (int k = 0; k < 2; ++k) dst[n][k] = *(const PG8_LAS bf16x8*)(lds + PG8_SB(b, h) + boff + n * 2048 + k * 1024); } while (0)
; #define PG8_MMA(ai, bj, At, Bt) do { __builtin_amdgcn_s_setprio(1); _Pragma("unroll") for (int m = 0; m < 4; ++m) _Pragma("unroll") for (int n = 0; n < 2; ++n) _Pragma("unroll") for (int k = 0; k < 2; ++k) \
;         acc[ai][bj][m][n] = __builtin_amdgcn_mfma_f32_16x16x32_bf16(Bt[n][k], At[m][k], acc[ai][bj][m][n], 0, 0, 0); __builtin_amdgcn_s_setprio(0); } while (0)
; #define PG8_WAIT_V(n) asm volatile("s_waitcnt vmcnt(" #n ")" ::: "memory")
; #define PG8_WAIT_L(n) asm volatile("s_waitcnt lgkmcnt(" #n ")" ::: "memory")
; #define PG8_BAR __builtin_amdgcn_s_barrier()
; #define PG8_SCHED __builtin_amdgcn_sched_barrier(0)
; template <class Epi, class Sched, bool ALIGN_EPI = false, bool SP2 = false>
; __device__ __forceinline__ void gemm_phase(PG8_LAS unsigned char* lds, const Gemm g, const Sched& S, const Epi& E) {
;     ...
;             PG8_LDB(B0, 1, 0); PG8_LDB(B1, 1, 1); PG8_SCHED; PG8_LDA(At, 1, 0); PG8_STAGE(PG8_SA(0, 1), a2 + hstep, voffA);
;             PG8_WAIT_V(8); PG8_WAIT_L(0); PG8_BAR; PG8_MMA(0, 0, At, B0); PG8_MMA(0, 1, At, B1); PG8_BAR; PG8_SCHED;
;             PG8_LDA(At, 1, 1); PG8_STAGE(PG8_SB(1, 0), b3, voffB); PG8_STAGE(PG8_SB(1, 1), b3 + hstep, voffB); PG8_STAGE(PG8_SA(1, 0), a3, voffA);
;             PG8_WAIT_V(8); PG8_WAIT_L(0); PG8_BAR; PG8_MMA(1, 0, At, B0); PG8_MMA(1, 1, At, B1); PG8_BAR; PG8_SCHED;
	s_add_i32 s18, s18, s56
	v_lshl_add_u64 v[206:207], v[206:207], 0, s[24:25]
	s_mov_b32 m0, s18
	ds_read_b128 v[174:177], v173 offset:49152
	ds_read_b128 v[178:181], v173 offset:50176
	ds_read_b128 v[182:185], v173 offset:51200
	ds_read_b128 v[186:189], v173 offset:52224
	ds_read_b128 v[190:193], v173 offset:53248
	ds_read_b128 v[194:197], v173 offset:54272
	ds_read_b128 v[198:201], v173 offset:55296
	ds_read_b128 v[202:205], v173 offset:56320
	global_load_lds_dwordx4 v[206:207], off
	s_add_i32 m0, s18, 0x2000
	s_add_u32 s52, s52, 0x40080
	v_lshl_add_u64 v[206:207], v[212:213], 0, s[24:25]
	s_addc_u32 s53, s53, 0
	s_add_i32 s18, s19, s56
	global_load_lds_dwordx4 v[206:207], off
	v_lshl_add_u64 v[206:207], s[52:53], 0, v[208:209]
	s_mov_b32 m0, s18
	s_nop 0
	global_load_lds_dwordx4 v[206:207], off
	v_lshl_add_u64 v[206:207], s[52:53], 0, v[152:153]
	s_add_i32 m0, s18, 0x2000
	s_nop 0
	global_load_lds_dwordx4 v[206:207], off
	v_lshl_add_u64 v[206:207], v[214:215], 0, s[24:25]
	s_mov_b32 m0, s61
	s_nop 0
	global_load_lds_dwordx4 v[206:207], off
	v_lshl_add_u64 v[206:207], v[218:219], 0, s[24:25]
	s_mov_b32 m0, s62
	s_nop 0
	global_load_lds_dwordx4 v[206:207], off
	s_waitcnt vmcnt(8)
	s_waitcnt lgkmcnt(0)
	s_setprio 1
	s_barrier
	v_mfma_f32_16x16x32_bf16 v[60:63], v[128:131], v[174:177], v[60:63]
	v_mfma_f32_16x16x32_bf16 v[56:59], v[136:139], v[174:177], v[56:59]
	v_mfma_f32_16x16x32_bf16 v[48:51], v[128:131], v[182:185], v[48:51]
	v_mfma_f32_16x16x32_bf16 v[40:43], v[136:139], v[182:185], v[40:43]
	v_mfma_f32_16x16x32_bf16 v[32:35], v[128:131], v[190:193], v[32:35]
	v_mfma_f32_16x16x32_bf16 v[24:27], v[136:139], v[190:193], v[24:27]
	v_mfma_f32_16x16x32_bf16 v[16:19], v[128:131], v[198:201], v[16:19]
	v_mfma_f32_16x16x32_bf16 v[8:11], v[136:139], v[198:201], v[8:11]
	v_mfma_f32_16x16x32_bf16 v[60:63], v[132:135], v[178:181], v[60:63]
	v_mfma_f32_16x16x32_bf16 v[56:59], v[140:143], v[178:181], v[56:59]
	v_mfma_f32_16x16x32_bf16 v[48:51], v[132:135], v[186:189], v[48:51]
	v_mfma_f32_16x16x32_bf16 v[40:43], v[140:143], v[186:189], v[40:43]
	v_mfma_f32_16x16x32_bf16 v[32:35], v[132:135], v[194:197], v[32:35]
	v_mfma_f32_16x16x32_bf16 v[24:27], v[140:143], v[194:197], v[24:27]
	v_mfma_f32_16x16x32_bf16 v[16:19], v[132:135], v[202:205], v[16:19]
	v_mfma_f32_16x16x32_bf16 v[8:11], v[140:143], v[202:205], v[8:11]
	s_setprio 0
	s_setprio 1
	v_mfma_f32_16x16x32_bf16 v[52:55], v[144:147], v[174:177], v[52:55]
	v_mfma_f32_16x16x32_bf16 v[44:47], v[162:165], v[174:177], v[44:47]
	v_mfma_f32_16x16x32_bf16 v[36:39], v[144:147], v[182:185], v[36:39]
	v_mfma_f32_16x16x32_bf16 v[28:31], v[162:165], v[182:185], v[28:31]
	v_mfma_f32_16x16x32_bf16 v[20:23], v[144:147], v[190:193], v[20:23]
	v_mfma_f32_16x16x32_bf16 v[12:15], v[162:165], v[190:193], v[12:15]
	v_mfma_f32_16x16x32_bf16 v[4:7], v[144:147], v[198:201], v[4:7]
	v_mfma_f32_16x16x32_bf16 v[0:3], v[162:165], v[198:201], v[0:3]
	v_mfma_f32_16x16x32_bf16 v[52:55], v[158:161], v[178:181], v[52:55]
	v_mfma_f32_16x16x32_bf16 v[44:47], v[166:169], v[178:181], v[44:47]
	v_mfma_f32_16x16x32_bf16 v[36:39], v[158:161], v[186:189], v[36:39]
	v_mfma_f32_16x16x32_bf16 v[28:31], v[166:169], v[186:189], v[28:31]
	v_mfma_f32_16x16x32_bf16 v[20:23], v[158:161], v[194:197], v[20:23]
	v_mfma_f32_16x16x32_bf16 v[12:15], v[166:169], v[194:197], v[12:15]
	v_mfma_f32_16x16x32_bf16 v[4:7], v[158:161], v[202:205], v[4:7]
	v_mfma_f32_16x16x32_bf16 v[0:3], v[166:169], v[202:205], v[0:3]
	s_setprio 0
	s_barrier
	s_add_i32 s68, s68, 2
	s_add_u32 s50, s50, 0x100
	s_addc_u32 s51, s51, 0
	s_add_u32 s66, s66, 0x100
	s_addc_u32 s67, s67, 0
	s_cmp_gt_u32 s68, 13
	s_cbranch_scc0 .LBB0_138
	s_and_b64 vcc, exec, s[8:9]
	s_cbranch_vccz .LBB0_141
	s_barrier

; #define PG8_STAGE(bufoff, gbase, voff) do { _Pragma("unroll") for (int _i = 0; _i < 2; ++_i) \
;         __builtin_amdgcn_global_load_lds((const unsigned*)((const char*)(gbase) + (voff)[_i]), (PG8_LAS unsigned*)(lds + (bufoff) + ldsw + _i * 8192), 16, 0, 0); } while (0)
; #define PG8_LDA(dst, b, h) do { _Pragma("unroll") for (int m = 0; m < 4; ++m) _Pragma("unroll") for (int k = 0; k < 2; ++k) dst[m][k] = *(const PG8_LAS bf16x8*)(lds + PG8_SA(b, h) + aoff + m * 2048 + k * 1024); } while (0)
; #define PG8_LDB(dst, b, h) do { _Pragma("unroll") for (int n = 0; n < 2; ++n) _Pragma("unroll") for (int k = 0; k < 2; ++k) dst[n][k] = *(const PG8_LAS bf16x8*)(lds + PG8_SB(b, h) + boff + n * 2048 + k * 1024); } while (0)
; #define PG8_WAIT_V(n) asm volatile("s_waitcnt vmcnt(" #n ")" ::: "memory")
; #define PG8_WAIT_L(n) asm volatile("s_waitcnt lgkmcnt(" #n ")" ::: "memory")
; #define PG8_BAR __builtin_amdgcn_s_barrier()
; #define PG8_SCHED __builtin_amdgcn_sched_barrier(0)
; template <class Epi, class Sched, bool ALIGN_EPI = false, bool SP2 = false>
; __device__ __forceinline__ void gemm_phase(PG8_LAS unsigned char* lds, const Gemm g, const Sched& S, const Epi& E) {
;     ...
;         const char* nA = has_next ? (const char*)g.A + S.a_byte(nxt, K) : cA; const char* nB = has_next ? (const char*)g.Bt + (size_t)nxt.pn * tstep : cB;
;         for (int t = 0; t < nt; t += 2) {
;             const bool last = (t == nt - 2);
;             const char* a1 = cA + (size_t)(t + 1) * kstep;
;             const char* a2 = last ? nA : cA + (size_t)(t + 2) * kstep; const char* b2 = last ? nB : cB + (size_t)(t + 2) * kstep;
;             const char* a3 = a2 + kstep; const char* b3 = b2 + kstep;
;             if (last && has_next) S.a_ready(nxt);
;             if constexpr (SP2) {
;             PG8_LDB(B0, 0, 0); PG8_LDB(B1, 0, 1); PG8_SCHED; PG8_LDA(At, 0, 0); PG8_STAGE(PG8_SA(1, 1), a1 + hstep, voffA);
;             PG8_WAIT_V(8); PG8_WAIT_L(0); PG8_BAR; PG8_MMA(0, 0, At, B0); PG8_MMA(0, 1, At, B1); PG8_BAR; PG8_SCHED;
;             PG8_LDA(At, 0, 1); PG8_STAGE(PG8_SB(0, 0), b2, voffB); PG8_STAGE(PG8_SB(0, 1), b2 + hstep, voffB); PG8_STAGE(PG8_SA(0, 0), a2, voffA);
;             PG8_WAIT_V(8); PG8_WAIT_L(0); PG8_BAR; PG8_MMA(1, 0, At, B0); PG8_MMA(1, 1, At, B1); PG8_BAR; PG8_SCHED;
.LBB0_162:
	s_add_u32 s18, s48, 0xfffc0080
	s_addc_u32 s19, s49, -1
	s_add_i32 s67, 0, 0x10000
	s_cmp_eq_u32 s66, 12
	s_cselect_b32 s53, s21, s19
	s_cselect_b32 s52, s47, s18
	s_cselect_b32 s51, s9, s65
	s_cselect_b32 s50, s63, s64
	s_add_i32 s18, 0, 0x14000
	v_add_u32_e32 v140, s67, v205
	v_add_u32_e32 v156, s18, v205
	ds_read_b128 v[128:131], v140
	ds_read_b128 v[132:135], v140 offset:1024
	ds_read_b128 v[136:139], v140 offset:2048
	ds_read_b128 v[140:143], v140 offset:3072
	ds_read_b128 v[144:147], v156
	ds_read_b128 v[148:151], v156 offset:1024
	ds_read_b128 v[152:155], v156 offset:2048
	ds_read_b128 v[156:159], v156 offset:3072
	v_lshl_add_u64 v[202:203], s[48:49], 0, v[190:191]
	s_add_i32 m0, s55, 0xc000
	ds_read_b128 v[160:163], v207
	ds_read_b128 v[164:167], v207 offset:1024
	ds_read_b128 v[168:171], v207 offset:2048
	ds_read_b128 v[172:175], v207 offset:3072
	ds_read_b128 v[176:179], v207 offset:4096
	ds_read_b128 v[180:183], v207 offset:5120
	ds_read_b128 v[194:197], v207 offset:6144
	ds_read_b128 v[198:201], v207 offset:7168
	global_load_lds_dwordx4 v[202:203], off
	v_lshl_add_u64 v[202:203], s[48:49], 0, v[192:193]
	s_add_i32 m0, s55, 0xe000
	s_nop 0
	global_load_lds_dwordx4 v[202:203], off
	s_waitcnt vmcnt(8)
	s_waitcnt lgkmcnt(0)
	s_setprio 1
	s_barrier
	v_mfma_f32_16x16x32_bf16 v[124:127], v[128:131], v[160:163], v[124:127]
	v_mfma_f32_16x16x32_bf16 v[120:123], v[136:139], v[160:163], v[120:123]
	v_mfma_f32_16x16x32_bf16 v[108:111], v[128:131], v[168:171], v[108:111]
	v_mfma_f32_16x16x32_bf16 v[104:107], v[136:139], v[168:171], v[104:107]
	v_mfma_f32_16x16x32_bf16 v[92:95], v[128:131], v[176:179], v[92:95]
	v_mfma_f32_16x16x32_bf16 v[88:91], v[136:139], v[176:179], v[88:91]
	v_mfma_f32_16x16x32_bf16 v[76:79], v[128:131], v[194:197], v[76:79]
	v_mfma_f32_16x16x32_bf16 v[72:75], v[136:139], v[194:197], v[72:75]
	v_mfma_f32_16x16x32_bf16 v[124:127], v[132:135], v[164:167], v[124:127]
	v_mfma_f32_16x16x32_bf16 v[120:123], v[140:143], v[164:167], v[120:123]
	v_mfma_f32_16x16x32_bf16 v[108:111], v[132:135], v[172:175], v[108:111]
	v_mfma_f32_16x16x32_bf16 v[104:107], v[140:143], v[172:175], v[104:107]
	v_mfma_f32_16x16x32_bf16 v[92:95], v[132:135], v[180:183], v[92:95]
	v_mfma_f32_16x16x32_bf16 v[88:91], v[140:143], v[180:183], v[88:91]
	v_mfma_f32_16x16x32_bf16 v[76:79], v[132:135], v[198:201], v[76:79]
	v_mfma_f32_16x16x32_bf16 v[72:75], v[140:143], v[198:201], v[72:75]
	s_setprio 0
	s_setprio 1
	v_mfma_f32_16x16x32_bf16 v[116:119], v[144:147], v[160:163], v[116:119]
	v_mfma_f32_16x16x32_bf16 v[112:115], v[152:155], v[160:163], v[112:115]
	v_mfma_f32_16x16x32_bf16 v[100:103], v[144:147], v[168:171], v[100:103]
	v_mfma_f32_16x16x32_bf16 v[96:99], v[152:155], v[168:171], v[96:99]
	v_mfma_f32_16x16x32_bf16 v[84:87], v[144:147], v[176:179], v[84:87]
	v_mfma_f32_16x16x32_bf16 v[80:83], v[152:155], v[176:179], v[80:83]
	v_mfma_f32_16x16x32_bf16 v[68:71], v[144:147], v[194:197], v[68:71]
	v_mfma_f32_16x16x32_bf16 v[64:67], v[152:155], v[194:197], v[64:67]
	v_mfma_f32_16x16x32_bf16 v[116:119], v[148:151], v[164:167], v[116:119]
	v_mfma_f32_16x16x32_bf16 v[112:115], v[156:159], v[164:167], v[112:115]
	v_mfma_f32_16x16x32_bf16 v[100:103], v[148:151], v[172:175], v[100:103]
	v_mfma_f32_16x16x32_bf16 v[96:99], v[156:159], v[172:175], v[96:99]
	v_mfma_f32_16x16x32_bf16 v[84:87], v[148:151], v[180:183], v[84:87]
	v_mfma_f32_16x16x32_bf16 v[80:83], v[156:159], v[180:183], v[80:83]
	v_mfma_f32_16x16x32_bf16 v[68:71], v[148:151], v[198:201], v[68:71]
	v_mfma_f32_16x16x32_bf16 v[64:67], v[156:159], v[198:201], v[64:67]
	s_setprio 0
	s_barrier
	s_add_i32 s19, s67, s54
	v_lshl_add_u64 v[202:203], s[50:51], 0, v[208:209]
	s_mov_b32 m0, s19
	ds_read_b128 v[160:163], v207 offset:16384
	ds_read_b128 v[164:167], v207 offset:17408
	ds_read_b128 v[168:171], v207 offset:18432
	ds_read_b128 v[172:175], v207 offset:19456
	ds_read_b128 v[176:179], v207 offset:20480
	ds_read_b128 v[180:183], v207 offset:21504
	ds_read_b128 v[194:197], v207 offset:22528
	ds_read_b128 v[198:201], v207 offset:23552
	global_load_lds_dwordx4 v[202:203], off
	s_add_i32 m0, s19, 0x2000
	s_add_u32 s68, s50, 0x40000
	v_lshl_add_u64 v[212:213], s[50:51], 0, v[188:189]
	s_addc_u32 s69, s51, 0
	s_add_i32 s18, s18, s54
	global_load_lds_dwordx4 v[212:213], off
	v_lshl_add_u64 v[214:215], s[68:69], 0, v[208:209]
	s_mov_b32 m0, s18
	v_lshl_add_u64 v[218:219], s[52:53], 0, v[186:187]
	global_load_lds_dwordx4 v[214:215], off
	v_lshl_add_u64 v[214:215], s[68:69], 0, v[188:189]
	s_add_i32 m0, s18, 0x2000
	s_nop 0
	global_load_lds_dwordx4 v[214:215], off
	v_lshl_add_u64 v[214:215], s[52:53], 0, v[184:185]
	s_mov_b32 m0, s55
	s_nop 0
	global_load_lds_dwordx4 v[214:215], off
	s_mov_b32 m0, s56
	s_nop 0
	global_load_lds_dwordx4 v[218:219], off
	s_waitcnt vmcnt(8)
	s_waitcnt lgkmcnt(0)
	s_setprio 1
	s_barrier
; #define PG8_STAGE(bufoff, gbase, voff) do { _Pragma("unroll") for (int _i = 0; _i < 2; ++_i) \
;         __builtin_amdgcn_global_load_lds((const unsigned*)((const char*)(gbase) + (voff)[_i]), (PG8_LAS unsigned*)(lds + (bufoff) + ldsw + _i * 8192), 16, 0, 0); } while (0)
; #define PG8_LDA(dst, b, h) do { _Pragma("unroll") for (int m = 0; m < 4; ++m) _Pragma("unroll") for (int k = 0; k < 2; ++k) dst[m][k] = *(const PG8_LAS bf16x8*)(lds + PG8_SA(b, h) + aoff + m * 2048 + k * 1024); } while (0)
; #define PG8_LDB(dst, b, h) do { _Pragma("unroll") for (int n = 0; n < 2; ++n) _Pragma("unroll") for (int k = 0; k < 2; ++k) dst[n][k] = *(const PG8_LAS bf16x8*)(lds + PG8_SB(b, h) + boff + n * 2048 + k * 1024); } while (0)
; #define PG8_MMA(ai, bj, At, Bt) do { __builtin_amdgcn_s_setprio(1); _Pragma("unroll") for (int m = 0; m < 4; ++m) _Pragma("unroll") for (int n = 0; n < 2; ++n) _Pragma("unroll") for (int k = 0; k < 2; ++k) \
;         acc[ai][bj][m][n] = __builtin_amdgcn_mfma_f32_16x16x32_bf16(Bt[n][k], At[m][k], acc[ai][bj][m][n], 0, 0, 0); __builtin_amdgcn_s_setprio(0); } while (0)
; #define PG8_WAIT_V(n) asm volatile("s_waitcnt vmcnt(" #n ")" ::: "memory")
; #define PG8_WAIT_L(n) asm volatile("s_waitcnt lgkmcnt(" #n ")" ::: "memory")
; #define PG8_BAR __builtin_amdgcn_s_barrier()
; #define PG8_SCHED __builtin_amdgcn_sched_barrier(0)
; template <class Epi, class Sched, bool ALIGN_EPI = false, bool SP2 = false>
; __device__ __forceinline__ void gemm_phase(PG8_LAS unsigned char* lds, const Gemm g, const Sched& S, const Epi& E) {
;     ...
;             PG8_LDA(At, 0, 1); PG8_STAGE(PG8_SB(0, 0), b2, voffB); PG8_STAGE(PG8_SB(0, 1), b2 + hstep, voffB); PG8_STAGE(PG8_SA(0, 0), a2, voffA);
;             PG8_WAIT_V(8); PG8_WAIT_L(0); PG8_BAR; PG8_MMA(1, 0, At, B0); PG8_MMA(1, 1, At, B1); PG8_BAR; PG8_SCHED;
;             PG8_LDB(B0, 1, 0); PG8_LDB(B1, 1, 1); PG8_SCHED; PG8_LDA(At, 1, 0); PG8_STAGE(PG8_SA(0, 1), a2 + hstep, voffA);
;             PG8_WAIT_V(8); PG8_WAIT_L(0); PG8_BAR; PG8_MMA(0, 0, At, B0); PG8_MMA(0, 1, At, B1); PG8_BAR; PG8_SCHED;
	v_mfma_f32_16x16x32_bf16 v[60:63], v[128:131], v[160:163], v[60:63]
	v_mfma_f32_16x16x32_bf16 v[56:59], v[136:139], v[160:163], v[56:59]
	v_mfma_f32_16x16x32_bf16 v[44:47], v[128:131], v[168:171], v[44:47]
	v_mfma_f32_16x16x32_bf16 v[40:43], v[136:139], v[168:171], v[40:43]
	v_mfma_f32_16x16x32_bf16 v[28:31], v[128:131], v[176:179], v[28:31]
	v_mfma_f32_16x16x32_bf16 v[24:27], v[136:139], v[176:179], v[24:27]
	v_mfma_f32_16x16x32_bf16 v[12:15], v[128:131], v[194:197], v[12:15]
	v_mfma_f32_16x16x32_bf16 v[8:11], v[136:139], v[194:197], v[8:11]
	v_mfma_f32_16x16x32_bf16 v[60:63], v[132:135], v[164:167], v[60:63]
	v_mfma_f32_16x16x32_bf16 v[56:59], v[140:143], v[164:167], v[56:59]
	v_mfma_f32_16x16x32_bf16 v[44:47], v[132:135], v[172:175], v[44:47]
	v_mfma_f32_16x16x32_bf16 v[40:43], v[140:143], v[172:175], v[40:43]
	v_mfma_f32_16x16x32_bf16 v[28:31], v[132:135], v[180:183], v[28:31]
	v_mfma_f32_16x16x32_bf16 v[24:27], v[140:143], v[180:183], v[24:27]
	v_mfma_f32_16x16x32_bf16 v[12:15], v[132:135], v[198:201], v[12:15]
	v_mfma_f32_16x16x32_bf16 v[8:11], v[140:143], v[198:201], v[8:11]
	s_setprio 0
	s_setprio 1
	v_mfma_f32_16x16x32_bf16 v[52:55], v[144:147], v[160:163], v[52:55]
	v_mfma_f32_16x16x32_bf16 v[48:51], v[152:155], v[160:163], v[48:51]
	v_mfma_f32_16x16x32_bf16 v[36:39], v[144:147], v[168:171], v[36:39]
	v_mfma_f32_16x16x32_bf16 v[32:35], v[152:155], v[168:171], v[32:35]
	v_mfma_f32_16x16x32_bf16 v[20:23], v[144:147], v[176:179], v[20:23]
	v_mfma_f32_16x16x32_bf16 v[16:19], v[152:155], v[176:179], v[16:19]
	v_mfma_f32_16x16x32_bf16 v[4:7], v[144:147], v[194:197], v[4:7]
	v_mfma_f32_16x16x32_bf16 v[0:3], v[152:155], v[194:197], v[0:3]
	v_mfma_f32_16x16x32_bf16 v[52:55], v[148:151], v[164:167], v[52:55]
	v_mfma_f32_16x16x32_bf16 v[48:51], v[156:159], v[164:167], v[48:51]
	v_mfma_f32_16x16x32_bf16 v[36:39], v[148:151], v[172:175], v[36:39]
	v_mfma_f32_16x16x32_bf16 v[32:35], v[156:159], v[172:175], v[32:35]
	v_mfma_f32_16x16x32_bf16 v[20:23], v[148:151], v[180:183], v[20:23]
	v_mfma_f32_16x16x32_bf16 v[16:19], v[156:159], v[180:183], v[16:19]
	v_mfma_f32_16x16x32_bf16 v[4:7], v[148:151], v[198:201], v[4:7]
	v_mfma_f32_16x16x32_bf16 v[0:3], v[156:159], v[198:201], v[0:3]
	s_setprio 0
	s_barrier
	s_add_i32 s18, 0, 0x18000
	s_add_i32 s19, 0, 0x1c000
	v_add_u32_e32 v140, s18, v205
	v_add_u32_e32 v156, s19, v205
	ds_read_b128 v[128:131], v140
	ds_read_b128 v[132:135], v140 offset:1024
	ds_read_b128 v[136:139], v140 offset:2048
	ds_read_b128 v[140:143], v140 offset:3072
	ds_read_b128 v[144:147], v156
	ds_read_b128 v[148:151], v156 offset:1024
	ds_read_b128 v[152:155], v156 offset:2048
	ds_read_b128 v[156:159], v156 offset:3072
	s_add_u32 s52, s52, 0x40000
	s_addc_u32 s53, s53, 0
	s_mov_b32 m0, s57
	v_lshl_add_u64 v[220:221], s[52:53], 0, v[184:185]
	ds_read_b128 v[160:163], v207 offset:32768
	ds_read_b128 v[164:167], v207 offset:33792
	ds_read_b128 v[168:171], v207 offset:34816
	ds_read_b128 v[172:175], v207 offset:35840
	ds_read_b128 v[176:179], v207 offset:36864
	ds_read_b128 v[180:183], v207 offset:37888
	ds_read_b128 v[194:197], v207 offset:38912
	ds_read_b128 v[198:201], v207 offset:39936
	global_load_lds_dwordx4 v[220:221], off
	v_lshl_add_u64 v[220:221], s[52:53], 0, v[186:187]
	s_mov_b32 m0, s58
	s_nop 0
	global_load_lds_dwordx4 v[220:221], off
	s_waitcnt vmcnt(8)
	s_waitcnt lgkmcnt(0)
	s_setprio 1
	s_barrier
	v_mfma_f32_16x16x32_bf16 v[124:127], v[128:131], v[160:163], v[124:127]
	v_mfma_f32_16x16x32_bf16 v[120:123], v[136:139], v[160:163], v[120:123]
	v_mfma_f32_16x16x32_bf16 v[108:111], v[128:131], v[168:171], v[108:111]
	v_mfma_f32_16x16x32_bf16 v[104:107], v[136:139], v[168:171], v[104:107]
	v_mfma_f32_16x16x32_bf16 v[92:95], v[128:131], v[176:179], v[92:95]
	v_mfma_f32_16x16x32_bf16 v[88:91], v[136:139], v[176:179], v[88:91]
	v_mfma_f32_16x16x32_bf16 v[76:79], v[128:131], v[194:197], v[76:79]
	v_mfma_f32_16x16x32_bf16 v[72:75], v[136:139], v[194:197], v[72:75]
	v_mfma_f32_16x16x32_bf16 v[124:127], v[132:135], v[164:167], v[124:127]
	v_mfma_f32_16x16x32_bf16 v[120:123], v[140:143], v[164:167], v[120:123]
	v_mfma_f32_16x16x32_bf16 v[108:111], v[132:135], v[172:175], v[108:111]
	v_mfma_f32_16x16x32_bf16 v[104:107], v[140:143], v[172:175], v[104:107]
	v_mfma_f32_16x16x32_bf16 v[92:95], v[132:135], v[180:183], v[92:95]
	v_mfma_f32_16x16x32_bf16 v[88:91], v[140:143], v[180:183], v[88:91]
	v_mfma_f32_16x16x32_bf16 v[76:79], v[132:135], v[198:201], v[76:79]
	v_mfma_f32_16x16x32_bf16 v[72:75], v[140:143], v[198:201], v[72:75]
	s_setprio 0
	s_setprio 1
	v_mfma_f32_16x16x32_bf16 v[116:119], v[144:147], v[160:163], v[116:119]
	v_mfma_f32_16x16x32_bf16 v[112:115], v[152:155], v[160:163], v[112:115]
	v_mfma_f32_16x16x32_bf16 v[100:103], v[144:147], v[168:171], v[100:103]
	v_mfma_f32_16x16x32_bf16 v[96:99], v[152:155], v[168:171], v[96:99]
	v_mfma_f32_16x16x32_bf16 v[84:87], v[144:147], v[176:179], v[84:87]
	v_mfma_f32_16x16x32_bf16 v[80:83], v[152:155], v[176:179], v[80:83]
	v_mfma_f32_16x16x32_bf16 v[68:71], v[144:147], v[194:197], v[68:71]
	v_mfma_f32_16x16x32_bf16 v[64:67], v[152:155], v[194:197], v[64:67]
	v_mfma_f32_16x16x32_bf16 v[116:119], v[148:151], v[164:167], v[116:119]
	v_mfma_f32_16x16x32_bf16 v[112:115], v[156:159], v[164:167], v[112:115]
	v_mfma_f32_16x16x32_bf16 v[100:103], v[148:151], v[172:175], v[100:103]
	v_mfma_f32_16x16x32_bf16 v[96:99], v[156:159], v[172:175], v[96:99]
	v_mfma_f32_16x16x32_bf16 v[84:87], v[148:151], v[180:183], v[84:87]
	v_mfma_f32_16x16x32_bf16 v[80:83], v[156:159], v[180:183], v[80:83]
	v_mfma_f32_16x16x32_bf16 v[68:71], v[148:151], v[198:201], v[68:71]
	v_mfma_f32_16x16x32_bf16 v[64:67], v[156:159], v[198:201], v[64:67]
	s_setprio 0
	s_barrier
; #define PG8_STAGE(bufoff, gbase, voff) do { _Pragma("unroll") for (int _i = 0; _i < 2; ++_i) \
;         __builtin_amdgcn_global_load_lds((const unsigned*)((const char*)(gbase) + (voff)[_i]), (PG8_LAS unsigned*)(lds + (bufoff) + ldsw + _i * 8192), 16, 0, 0); } while (0)
; #define PG8_LDA(dst, b, h) do { _Pragma("unroll") for (int m = 0; m < 4; ++m) _Pragma("unroll") for (int k = 0; k < 2; ++k) dst[m][k] = *(const PG8_LAS bf16x8*)(lds + PG8_SA(b, h) + aoff + m * 2048 + k * 1024); } while (0)
; #define PG8_LDB(dst, b, h) do { _Pragma("unroll") for (int n = 0; n < 2; ++n) _Pragma("unroll") for (int k = 0; k < 2; ++k) dst[n][k] = *(const PG8_LAS bf16x8*)(lds + PG8_SB(b, h) + boff + n * 2048 + k * 1024); } while (0)
; #define PG8_MMA(ai, bj, At, Bt) do { __builtin_amdgcn_s_setprio(1); _Pragma("unroll") for (int m = 0; m < 4; ++m) _Pragma("unroll") for (int n = 0; n < 2; ++n) _Pragma("unroll") for (int k = 0; k < 2; ++k) \
;         acc[ai][bj][m][n] = __builtin_amdgcn_mfma_f32_16x16x32_bf16(Bt[n][k], At[m][k], acc[ai][bj][m][n], 0, 0, 0); __builtin_amdgcn_s_setprio(0); } while (0)
; #define PG8_WAIT_V(n) asm volatile("s_waitcnt vmcnt(" #n ")" ::: "memory")
; #define PG8_WAIT_L(n) asm volatile("s_waitcnt lgkmcnt(" #n ")" ::: "memory")
; #define PG8_BAR __builtin_amdgcn_s_barrier()
; #define PG8_SCHED __builtin_amdgcn_sched_barrier(0)
; template <class Epi, class Sched, bool ALIGN_EPI = false, bool SP2 = false>
; __device__ __forceinline__ void gemm_phase(PG8_LAS unsigned char* lds, const Gemm g, const Sched& S, const Epi& E) {
;     ...
;             PG8_LDB(B0, 1, 0); PG8_LDB(B1, 1, 1); PG8_SCHED; PG8_LDA(At, 1, 0); PG8_STAGE(PG8_SA(0, 1), a2 + hstep, voffA);
;             PG8_WAIT_V(8); PG8_WAIT_L(0); PG8_BAR; PG8_MMA(0, 0, At, B0); PG8_MMA(0, 1, At, B1); PG8_BAR; PG8_SCHED;
;             PG8_LDA(At, 1, 1); PG8_STAGE(PG8_SB(1, 0), b3, voffB); PG8_STAGE(PG8_SB(1, 1), b3 + hstep, voffB); PG8_STAGE(PG8_SA(1, 0), a3, voffA);
;             PG8_WAIT_V(8); PG8_WAIT_L(0); PG8_BAR; PG8_MMA(1, 0, At, B0); PG8_MMA(1, 1, At, B1); PG8_BAR; PG8_SCHED;
	s_add_i32 s18, s18, s54
	v_lshl_add_u64 v[202:203], v[202:203], 0, s[24:25]
	s_mov_b32 m0, s18
	ds_read_b128 v[160:163], v207 offset:49152
	ds_read_b128 v[164:167], v207 offset:50176
	ds_read_b128 v[168:171], v207 offset:51200
	ds_read_b128 v[172:175], v207 offset:52224
	ds_read_b128 v[176:179], v207 offset:53248
	ds_read_b128 v[180:183], v207 offset:54272
	ds_read_b128 v[194:197], v207 offset:55296
	ds_read_b128 v[198:201], v207 offset:56320
	global_load_lds_dwordx4 v[202:203], off
	s_add_i32 m0, s18, 0x2000
	s_add_u32 s50, s50, 0x40080
	v_lshl_add_u64 v[202:203], v[212:213], 0, s[24:25]
	s_addc_u32 s51, s51, 0
	s_add_i32 s18, s19, s54
	global_load_lds_dwordx4 v[202:203], off
	v_lshl_add_u64 v[202:203], s[50:51], 0, v[208:209]
	s_mov_b32 m0, s18
	s_nop 0
	global_load_lds_dwordx4 v[202:203], off
	v_lshl_add_u64 v[202:203], s[50:51], 0, v[188:189]
	s_add_i32 m0, s18, 0x2000
	s_nop 0
	global_load_lds_dwordx4 v[202:203], off
	v_lshl_add_u64 v[202:203], v[214:215], 0, s[24:25]
	s_mov_b32 m0, s59
	s_nop 0
	global_load_lds_dwordx4 v[202:203], off
	v_lshl_add_u64 v[202:203], v[218:219], 0, s[24:25]
	s_mov_b32 m0, s60
	s_nop 0
	global_load_lds_dwordx4 v[202:203], off
	s_waitcnt vmcnt(8)
	s_waitcnt lgkmcnt(0)
	s_setprio 1
	s_barrier
	v_mfma_f32_16x16x32_bf16 v[60:63], v[128:131], v[160:163], v[60:63]
	v_mfma_f32_16x16x32_bf16 v[56:59], v[136:139], v[160:163], v[56:59]
	v_mfma_f32_16x16x32_bf16 v[44:47], v[128:131], v[168:171], v[44:47]
	v_mfma_f32_16x16x32_bf16 v[40:43], v[136:139], v[168:171], v[40:43]
	v_mfma_f32_16x16x32_bf16 v[28:31], v[128:131], v[176:179], v[28:31]
	v_mfma_f32_16x16x32_bf16 v[24:27], v[136:139], v[176:179], v[24:27]
	v_mfma_f32_16x16x32_bf16 v[12:15], v[128:131], v[194:197], v[12:15]
	v_mfma_f32_16x16x32_bf16 v[8:11], v[136:139], v[194:197], v[8:11]
	v_mfma_f32_16x16x32_bf16 v[60:63], v[132:135], v[164:167], v[60:63]
	v_mfma_f32_16x16x32_bf16 v[56:59], v[140:143], v[164:167], v[56:59]
	v_mfma_f32_16x16x32_bf16 v[44:47], v[132:135], v[172:175], v[44:47]
	v_mfma_f32_16x16x32_bf16 v[40:43], v[140:143], v[172:175], v[40:43]
	v_mfma_f32_16x16x32_bf16 v[28:31], v[132:135], v[180:183], v[28:31]
	v_mfma_f32_16x16x32_bf16 v[24:27], v[140:143], v[180:183], v[24:27]
	v_mfma_f32_16x16x32_bf16 v[12:15], v[132:135], v[198:201], v[12:15]
	v_mfma_f32_16x16x32_bf16 v[8:11], v[140:143], v[198:201], v[8:11]
	s_setprio 0
	s_setprio 1
	v_mfma_f32_16x16x32_bf16 v[52:55], v[144:147], v[160:163], v[52:55]
	v_mfma_f32_16x16x32_bf16 v[48:51], v[152:155], v[160:163], v[48:51]
	v_mfma_f32_16x16x32_bf16 v[36:39], v[144:147], v[168:171], v[36:39]
	v_mfma_f32_16x16x32_bf16 v[32:35], v[152:155], v[168:171], v[32:35]
	v_mfma_f32_16x16x32_bf16 v[20:23], v[144:147], v[176:179], v[20:23]
	v_mfma_f32_16x16x32_bf16 v[16:19], v[152:155], v[176:179], v[16:19]
	v_mfma_f32_16x16x32_bf16 v[4:7], v[144:147], v[194:197], v[4:7]
	v_mfma_f32_16x16x32_bf16 v[0:3], v[152:155], v[194:197], v[0:3]
	v_mfma_f32_16x16x32_bf16 v[52:55], v[148:151], v[164:167], v[52:55]
	v_mfma_f32_16x16x32_bf16 v[48:51], v[156:159], v[164:167], v[48:51]
	v_mfma_f32_16x16x32_bf16 v[36:39], v[148:151], v[172:175], v[36:39]
	v_mfma_f32_16x16x32_bf16 v[32:35], v[156:159], v[172:175], v[32:35]
	v_mfma_f32_16x16x32_bf16 v[20:23], v[148:151], v[180:183], v[20:23]
	v_mfma_f32_16x16x32_bf16 v[16:19], v[156:159], v[180:183], v[16:19]
	v_mfma_f32_16x16x32_bf16 v[4:7], v[148:151], v[198:201], v[4:7]
	v_mfma_f32_16x16x32_bf16 v[0:3], v[156:159], v[198:201], v[0:3]
	s_setprio 0
	s_barrier
	s_add_i32 s66, s66, 2
	s_add_u32 s48, s48, 0x100
	s_addc_u32 s49, s49, 0
	s_add_u32 s64, s64, 0x100
	s_addc_u32 s65, s65, 0
	s_cmp_gt_u32 s66, 13
	s_cbranch_scc0 .LBB0_162
	s_and_b64 vcc, exec, s[6:7]
	s_cbranch_vccz .LBB0_165
	s_barrier

; #define PG8_STAGE(bufoff, gbase, voff) do { _Pragma("unroll") for (int _i = 0; _i < 2; ++_i) \
;         __builtin_amdgcn_global_load_lds((const unsigned*)((const char*)(gbase) + (voff)[_i]), (PG8_LAS unsigned*)(lds + (bufoff) + ldsw + _i * 8192), 16, 0, 0); } while (0)
; #define PG8_LDA(dst, b, h) do { _Pragma("unroll") for (int m = 0; m < 4; ++m) _Pragma("unroll") for (int k = 0; k < 2; ++k) dst[m][k] = *(const PG8_LAS bf16x8*)(lds + PG8_SA(b, h) + aoff + m * 2048 + k * 1024); } while (0)
; #define PG8_LDB(dst, b, h) do { _Pragma("unroll") for (int n = 0; n < 2; ++n) _Pragma("unroll") for (int k = 0; k < 2; ++k) dst[n][k] = *(const PG8_LAS bf16x8*)(lds + PG8_SB(b, h) + boff + n * 2048 + k * 1024); } while (0)
; #define PG8_WAIT_V(n) asm volatile("s_waitcnt vmcnt(" #n ")" ::: "memory")
; #define PG8_WAIT_L(n) asm volatile("s_waitcnt lgkmcnt(" #n ")" ::: "memory")
; #define PG8_BAR __builtin_amdgcn_s_barrier()
; #define PG8_SCHED __builtin_amdgcn_sched_barrier(0)
; template <class Epi, class Sched, bool ALIGN_EPI = false, bool SP2 = false>
; __device__ __forceinline__ void gemm_phase(PG8_LAS unsigned char* lds, const Gemm g, const Sched& S, const Epi& E) {
;     ...
;         const char* nA = has_next ? (const char*)g.A + S.a_byte(nxt, K) : cA; const char* nB = has_next ? (const char*)g.Bt + (size_t)nxt.pn * tstep : cB;
;         for (int t = 0; t < nt; t += 2) {
;             const bool last = (t == nt - 2);
;             const char* a1 = cA + (size_t)(t + 1) * kstep;
;             const char* a2 = last ? nA : cA + (size_t)(t + 2) * kstep; const char* b2 = last ? nB : cB + (size_t)(t + 2) * kstep;
;             const char* a3 = a2 + kstep; const char* b3 = b2 + kstep;
;             if (last && has_next) S.a_ready(nxt);
;             if constexpr (SP2) {
;             PG8_LDB(B0, 0, 0); PG8_LDB(B1, 0, 1); PG8_SCHED; PG8_LDA(At, 0, 0); PG8_STAGE(PG8_SA(1, 1), a1 + hstep, voffA);
;             PG8_WAIT_V(8); PG8_WAIT_L(0); PG8_BAR; PG8_MMA(0, 0, At, B0); PG8_MMA(0, 1, At, B1); PG8_BAR; PG8_SCHED;
;             PG8_LDA(At, 0, 1); PG8_STAGE(PG8_SB(0, 0), b2, voffB); PG8_STAGE(PG8_SB(0, 1), b2 + hstep, voffB); PG8_STAGE(PG8_SA(0, 0), a2, voffA);
;             PG8_WAIT_V(8); PG8_WAIT_L(0); PG8_BAR; PG8_MMA(1, 0, At, B0); PG8_MMA(1, 1, At, B1); PG8_BAR; PG8_SCHED;
.LBB0_190:
	s_add_u32 s18, s48, 0xfffc0080
	s_addc_u32 s19, s49, -1
	s_add_i32 s67, 0, 0x10000
	s_cmp_eq_u32 s66, 12
	s_cselect_b32 s53, s11, s19
	s_cselect_b32 s52, s35, s18
	s_cselect_b32 s51, s9, s65
	s_cselect_b32 s50, s38, s47
	s_add_i32 s18, 0, 0x14000
	v_add_u32_e32 v158, s67, v147
	v_add_u32_e32 v174, s18, v147
	ds_read_b128 v[142:145], v158
	ds_read_b128 v[150:153], v158 offset:1024
	ds_read_b128 v[154:157], v158 offset:2048
	ds_read_b128 v[158:161], v158 offset:3072
	ds_read_b128 v[162:165], v174
	ds_read_b128 v[166:169], v174 offset:1024
	ds_read_b128 v[170:173], v174 offset:2048
	ds_read_b128 v[174:177], v174 offset:3072
	v_lshl_add_u64 v[206:207], s[48:49], 0, v[138:139]
	s_add_i32 m0, s57, 0xc000
	ds_read_b128 v[178:181], v149
	ds_read_b128 v[182:185], v149 offset:1024
	ds_read_b128 v[186:189], v149 offset:2048
	ds_read_b128 v[190:193], v149 offset:3072
	ds_read_b128 v[194:197], v149 offset:4096
	ds_read_b128 v[198:201], v149 offset:5120
	ds_read_b128 v[202:205], v149 offset:6144
	ds_read_b128 v[212:215], v149 offset:7168
	global_load_lds_dwordx4 v[206:207], off
	v_lshl_add_u64 v[206:207], s[48:49], 0, v[140:141]
	s_add_i32 m0, s57, 0xe000
	s_nop 0
	global_load_lds_dwordx4 v[206:207], off
	s_waitcnt vmcnt(8)
	s_waitcnt lgkmcnt(0)
	s_setprio 1
	s_barrier
	v_mfma_f32_16x16x32_bf16 v[124:127], v[142:145], v[178:181], v[124:127]
	v_mfma_f32_16x16x32_bf16 v[120:123], v[154:157], v[178:181], v[120:123]
	v_mfma_f32_16x16x32_bf16 v[108:111], v[142:145], v[186:189], v[108:111]
	v_mfma_f32_16x16x32_bf16 v[104:107], v[154:157], v[186:189], v[104:107]
	v_mfma_f32_16x16x32_bf16 v[92:95], v[142:145], v[194:197], v[92:95]
	v_mfma_f32_16x16x32_bf16 v[88:91], v[154:157], v[194:197], v[88:91]
	v_mfma_f32_16x16x32_bf16 v[76:79], v[142:145], v[202:205], v[76:79]
	v_mfma_f32_16x16x32_bf16 v[72:75], v[154:157], v[202:205], v[72:75]
	v_mfma_f32_16x16x32_bf16 v[124:127], v[150:153], v[182:185], v[124:127]
	v_mfma_f32_16x16x32_bf16 v[120:123], v[158:161], v[182:185], v[120:123]
	v_mfma_f32_16x16x32_bf16 v[108:111], v[150:153], v[190:193], v[108:111]
	v_mfma_f32_16x16x32_bf16 v[104:107], v[158:161], v[190:193], v[104:107]
	v_mfma_f32_16x16x32_bf16 v[92:95], v[150:153], v[198:201], v[92:95]
	v_mfma_f32_16x16x32_bf16 v[88:91], v[158:161], v[198:201], v[88:91]
	v_mfma_f32_16x16x32_bf16 v[76:79], v[150:153], v[212:215], v[76:79]
	v_mfma_f32_16x16x32_bf16 v[72:75], v[158:161], v[212:215], v[72:75]
	s_setprio 0
	s_setprio 1
	v_mfma_f32_16x16x32_bf16 v[116:119], v[162:165], v[178:181], v[116:119]
	v_mfma_f32_16x16x32_bf16 v[112:115], v[170:173], v[178:181], v[112:115]
	v_mfma_f32_16x16x32_bf16 v[100:103], v[162:165], v[186:189], v[100:103]
	v_mfma_f32_16x16x32_bf16 v[96:99], v[170:173], v[186:189], v[96:99]
	v_mfma_f32_16x16x32_bf16 v[84:87], v[162:165], v[194:197], v[84:87]
	v_mfma_f32_16x16x32_bf16 v[80:83], v[170:173], v[194:197], v[80:83]
	v_mfma_f32_16x16x32_bf16 v[68:71], v[162:165], v[202:205], v[68:71]
	v_mfma_f32_16x16x32_bf16 v[64:67], v[170:173], v[202:205], v[64:67]
	v_mfma_f32_16x16x32_bf16 v[116:119], v[166:169], v[182:185], v[116:119]
	v_mfma_f32_16x16x32_bf16 v[112:115], v[174:177], v[182:185], v[112:115]
	v_mfma_f32_16x16x32_bf16 v[100:103], v[166:169], v[190:193], v[100:103]
	v_mfma_f32_16x16x32_bf16 v[96:99], v[174:177], v[190:193], v[96:99]
	v_mfma_f32_16x16x32_bf16 v[84:87], v[166:169], v[198:201], v[84:87]
	v_mfma_f32_16x16x32_bf16 v[80:83], v[174:177], v[198:201], v[80:83]
	v_mfma_f32_16x16x32_bf16 v[68:71], v[166:169], v[212:215], v[68:71]
	v_mfma_f32_16x16x32_bf16 v[64:67], v[174:177], v[212:215], v[64:67]
	s_setprio 0
	s_barrier
	s_add_i32 s19, s67, s56
	v_lshl_add_u64 v[206:207], s[50:51], 0, v[130:131]
	s_mov_b32 m0, s19
	ds_read_b128 v[178:181], v149 offset:16384
	ds_read_b128 v[182:185], v149 offset:17408
	ds_read_b128 v[186:189], v149 offset:18432
	ds_read_b128 v[190:193], v149 offset:19456
	ds_read_b128 v[194:197], v149 offset:20480
	ds_read_b128 v[198:201], v149 offset:21504
	ds_read_b128 v[202:205], v149 offset:22528
	ds_read_b128 v[212:215], v149 offset:23552
	global_load_lds_dwordx4 v[206:207], off
	s_add_i32 m0, s19, 0x2000
	s_add_u32 s68, s50, 0x40000
	v_lshl_add_u64 v[218:219], s[50:51], 0, v[134:135]
	s_addc_u32 s69, s51, 0
	s_add_i32 s18, s18, s56
	global_load_lds_dwordx4 v[218:219], off
	v_lshl_add_u64 v[220:221], s[68:69], 0, v[130:131]
	s_mov_b32 m0, s18
	v_lshl_add_u64 v[222:223], s[52:53], 0, v[132:133]
	global_load_lds_dwordx4 v[220:221], off
	v_lshl_add_u64 v[220:221], s[68:69], 0, v[134:135]
	s_add_i32 m0, s18, 0x2000
	s_nop 0
	global_load_lds_dwordx4 v[220:221], off
	v_lshl_add_u64 v[220:221], s[52:53], 0, v[128:129]
	s_mov_b32 m0, s57
	s_nop 0
	global_load_lds_dwordx4 v[220:221], off
	s_mov_b32 m0, s58
	s_nop 0
	global_load_lds_dwordx4 v[222:223], off
	s_waitcnt vmcnt(8)
	s_waitcnt lgkmcnt(0)
	s_setprio 1
	s_barrier
; #define PG8_STAGE(bufoff, gbase, voff) do { _Pragma("unroll") for (int _i = 0; _i < 2; ++_i) \
;         __builtin_amdgcn_global_load_lds((const unsigned*)((const char*)(gbase) + (voff)[_i]), (PG8_LAS unsigned*)(lds + (bufoff) + ldsw + _i * 8192), 16, 0, 0); } while (0)
; #define PG8_LDA(dst, b, h) do { _Pragma("unroll") for (int m = 0; m < 4; ++m) _Pragma("unroll") for (int k = 0; k < 2; ++k) dst[m][k] = *(const PG8_LAS bf16x8*)(lds + PG8_SA(b, h) + aoff + m * 2048 + k * 1024); } while (0)
; #define PG8_LDB(dst, b, h) do { _Pragma("unroll") for (int n = 0; n < 2; ++n) _Pragma("unroll") for (int k = 0; k < 2; ++k) dst[n][k] = *(const PG8_LAS bf16x8*)(lds + PG8_SB(b, h) + boff + n * 2048 + k * 1024); } while (0)
; #define PG8_MMA(ai, bj, At, Bt) do { __builtin_amdgcn_s_setprio(1); _Pragma("unroll") for (int m = 0; m < 4; ++m) _Pragma("unroll") for (int n = 0; n < 2; ++n) _Pragma("unroll") for (int k = 0; k < 2; ++k) \
;         acc[ai][bj][m][n] = __builtin_amdgcn_mfma_f32_16x16x32_bf16(Bt[n][k], At[m][k], acc[ai][bj][m][n], 0, 0, 0); __builtin_amdgcn_s_setprio(0); } while (0)
; #define PG8_WAIT_V(n) asm volatile("s_waitcnt vmcnt(" #n ")" ::: "memory")
; #define PG8_WAIT_L(n) asm volatile("s_waitcnt lgkmcnt(" #n ")" ::: "memory")
; #define PG8_BAR __builtin_amdgcn_s_barrier()
; #define PG8_SCHED __builtin_amdgcn_sched_barrier(0)
; template <class Epi, class Sched, bool ALIGN_EPI = false, bool SP2 = false>
; __device__ __forceinline__ void gemm_phase(PG8_LAS unsigned char* lds, const Gemm g, const Sched& S, const Epi& E) {
;     ...
;             PG8_LDA(At, 0, 1); PG8_STAGE(PG8_SB(0, 0), b2, voffB); PG8_STAGE(PG8_SB(0, 1), b2 + hstep, voffB); PG8_STAGE(PG8_SA(0, 0), a2, voffA);
;             PG8_WAIT_V(8); PG8_WAIT_L(0); PG8_BAR; PG8_MMA(1, 0, At, B0); PG8_MMA(1, 1, At, B1); PG8_BAR; PG8_SCHED;
;             PG8_LDB(B0, 1, 0); PG8_LDB(B1, 1, 1); PG8_SCHED; PG8_LDA(At, 1, 0); PG8_STAGE(PG8_SA(0, 1), a2 + hstep, voffA);
;             PG8_WAIT_V(8); PG8_WAIT_L(0); PG8_BAR; PG8_MMA(0, 0, At, B0); PG8_MMA(0, 1, At, B1); PG8_BAR; PG8_SCHED;
	v_mfma_f32_16x16x32_bf16 v[60:63], v[142:145], v[178:181], v[60:63]
	v_mfma_f32_16x16x32_bf16 v[56:59], v[154:157], v[178:181], v[56:59]
	v_mfma_f32_16x16x32_bf16 v[44:47], v[142:145], v[186:189], v[44:47]
	v_mfma_f32_16x16x32_bf16 v[40:43], v[154:157], v[186:189], v[40:43]
	v_mfma_f32_16x16x32_bf16 v[28:31], v[142:145], v[194:197], v[28:31]
	v_mfma_f32_16x16x32_bf16 v[24:27], v[154:157], v[194:197], v[24:27]
	v_mfma_f32_16x16x32_bf16 v[12:15], v[142:145], v[202:205], v[12:15]
	v_mfma_f32_16x16x32_bf16 v[8:11], v[154:157], v[202:205], v[8:11]
	v_mfma_f32_16x16x32_bf16 v[60:63], v[150:153], v[182:185], v[60:63]
	v_mfma_f32_16x16x32_bf16 v[56:59], v[158:161], v[182:185], v[56:59]
	v_mfma_f32_16x16x32_bf16 v[44:47], v[150:153], v[190:193], v[44:47]
	v_mfma_f32_16x16x32_bf16 v[40:43], v[158:161], v[190:193], v[40:43]
	v_mfma_f32_16x16x32_bf16 v[28:31], v[150:153], v[198:201], v[28:31]
	v_mfma_f32_16x16x32_bf16 v[24:27], v[158:161], v[198:201], v[24:27]
	v_mfma_f32_16x16x32_bf16 v[12:15], v[150:153], v[212:215], v[12:15]
	v_mfma_f32_16x16x32_bf16 v[8:11], v[158:161], v[212:215], v[8:11]
	s_setprio 0
	s_setprio 1
	v_mfma_f32_16x16x32_bf16 v[52:55], v[162:165], v[178:181], v[52:55]
	v_mfma_f32_16x16x32_bf16 v[48:51], v[170:173], v[178:181], v[48:51]
	v_mfma_f32_16x16x32_bf16 v[36:39], v[162:165], v[186:189], v[36:39]
	v_mfma_f32_16x16x32_bf16 v[32:35], v[170:173], v[186:189], v[32:35]
	v_mfma_f32_16x16x32_bf16 v[20:23], v[162:165], v[194:197], v[20:23]
	v_mfma_f32_16x16x32_bf16 v[16:19], v[170:173], v[194:197], v[16:19]
	v_mfma_f32_16x16x32_bf16 v[4:7], v[162:165], v[202:205], v[4:7]
	v_mfma_f32_16x16x32_bf16 v[0:3], v[170:173], v[202:205], v[0:3]
	v_mfma_f32_16x16x32_bf16 v[52:55], v[166:169], v[182:185], v[52:55]
	v_mfma_f32_16x16x32_bf16 v[48:51], v[174:177], v[182:185], v[48:51]
	v_mfma_f32_16x16x32_bf16 v[36:39], v[166:169], v[190:193], v[36:39]
	v_mfma_f32_16x16x32_bf16 v[32:35], v[174:177], v[190:193], v[32:35]
	v_mfma_f32_16x16x32_bf16 v[20:23], v[166:169], v[198:201], v[20:23]
	v_mfma_f32_16x16x32_bf16 v[16:19], v[174:177], v[198:201], v[16:19]
	v_mfma_f32_16x16x32_bf16 v[4:7], v[166:169], v[212:215], v[4:7]
	v_mfma_f32_16x16x32_bf16 v[0:3], v[174:177], v[212:215], v[0:3]
	s_setprio 0
	s_barrier
	s_add_i32 s18, 0, 0x18000
	s_add_i32 s19, 0, 0x1c000
	v_add_u32_e32 v158, s18, v147
	v_add_u32_e32 v174, s19, v147
	ds_read_b128 v[142:145], v158
	ds_read_b128 v[150:153], v158 offset:1024
	ds_read_b128 v[154:157], v158 offset:2048
	ds_read_b128 v[158:161], v158 offset:3072
	ds_read_b128 v[162:165], v174
	ds_read_b128 v[166:169], v174 offset:1024
	ds_read_b128 v[170:173], v174 offset:2048
	ds_read_b128 v[174:177], v174 offset:3072
	s_add_u32 s52, s52, 0x40000
	s_addc_u32 s53, s53, 0
	s_mov_b32 m0, s59
	v_lshl_add_u64 v[224:225], s[52:53], 0, v[128:129]
	ds_read_b128 v[178:181], v149 offset:32768
	ds_read_b128 v[182:185], v149 offset:33792
	ds_read_b128 v[186:189], v149 offset:34816
	ds_read_b128 v[190:193], v149 offset:35840
	ds_read_b128 v[194:197], v149 offset:36864
	ds_read_b128 v[198:201], v149 offset:37888
	ds_read_b128 v[202:205], v149 offset:38912
	ds_read_b128 v[212:215], v149 offset:39936
	global_load_lds_dwordx4 v[224:225], off
	v_lshl_add_u64 v[224:225], s[52:53], 0, v[132:133]
	s_mov_b32 m0, s60
	s_nop 0
	global_load_lds_dwordx4 v[224:225], off
	s_waitcnt vmcnt(8)
	s_waitcnt lgkmcnt(0)
	s_setprio 1
	s_barrier
	v_mfma_f32_16x16x32_bf16 v[124:127], v[142:145], v[178:181], v[124:127]
	v_mfma_f32_16x16x32_bf16 v[120:123], v[154:157], v[178:181], v[120:123]
	v_mfma_f32_16x16x32_bf16 v[108:111], v[142:145], v[186:189], v[108:111]
	v_mfma_f32_16x16x32_bf16 v[104:107], v[154:157], v[186:189], v[104:107]
	v_mfma_f32_16x16x32_bf16 v[92:95], v[142:145], v[194:197], v[92:95]
	v_mfma_f32_16x16x32_bf16 v[88:91], v[154:157], v[194:197], v[88:91]
	v_mfma_f32_16x16x32_bf16 v[76:79], v[142:145], v[202:205], v[76:79]
	v_mfma_f32_16x16x32_bf16 v[72:75], v[154:157], v[202:205], v[72:75]
	v_mfma_f32_16x16x32_bf16 v[124:127], v[150:153], v[182:185], v[124:127]
	v_mfma_f32_16x16x32_bf16 v[120:123], v[158:161], v[182:185], v[120:123]
	v_mfma_f32_16x16x32_bf16 v[108:111], v[150:153], v[190:193], v[108:111]
	v_mfma_f32_16x16x32_bf16 v[104:107], v[158:161], v[190:193], v[104:107]
	v_mfma_f32_16x16x32_bf16 v[92:95], v[150:153], v[198:201], v[92:95]
	v_mfma_f32_16x16x32_bf16 v[88:91], v[158:161], v[198:201], v[88:91]
	v_mfma_f32_16x16x32_bf16 v[76:79], v[150:153], v[212:215], v[76:79]
	v_mfma_f32_16x16x32_bf16 v[72:75], v[158:161], v[212:215], v[72:75]
	s_setprio 0
	s_setprio 1
	v_mfma_f32_16x16x32_bf16 v[116:119], v[162:165], v[178:181], v[116:119]
	v_mfma_f32_16x16x32_bf16 v[112:115], v[170:173], v[178:181], v[112:115]
	v_mfma_f32_16x16x32_bf16 v[100:103], v[162:165], v[186:189], v[100:103]
	v_mfma_f32_16x16x32_bf16 v[96:99], v[170:173], v[186:189], v[96:99]
	v_mfma_f32_16x16x32_bf16 v[84:87], v[162:165], v[194:197], v[84:87]
	v_mfma_f32_16x16x32_bf16 v[80:83], v[170:173], v[194:197], v[80:83]
	v_mfma_f32_16x16x32_bf16 v[68:71], v[162:165], v[202:205], v[68:71]
	v_mfma_f32_16x16x32_bf16 v[64:67], v[170:173], v[202:205], v[64:67]
	v_mfma_f32_16x16x32_bf16 v[116:119], v[166:169], v[182:185], v[116:119]
	v_mfma_f32_16x16x32_bf16 v[112:115], v[174:177], v[182:185], v[112:115]
	v_mfma_f32_16x16x32_bf16 v[100:103], v[166:169], v[190:193], v[100:103]
	v_mfma_f32_16x16x32_bf16 v[96:99], v[174:177], v[190:193], v[96:99]
	v_mfma_f32_16x16x32_bf16 v[84:87], v[166:169], v[198:201], v[84:87]
	v_mfma_f32_16x16x32_bf16 v[80:83], v[174:177], v[198:201], v[80:83]
	v_mfma_f32_16x16x32_bf16 v[68:71], v[166:169], v[212:215], v[68:71]
	v_mfma_f32_16x16x32_bf16 v[64:67], v[174:177], v[212:215], v[64:67]
	s_setprio 0
	s_barrier
; #define PG8_STAGE(bufoff, gbase, voff) do { _Pragma("unroll") for (int _i = 0; _i < 2; ++_i) \
;         __builtin_amdgcn_global_load_lds((const unsigned*)((const char*)(gbase) + (voff)[_i]), (PG8_LAS unsigned*)(lds + (bufoff) + ldsw + _i * 8192), 16, 0, 0); } while (0)
; #define PG8_LDA(dst, b, h) do { _Pragma("unroll") for (int m = 0; m < 4; ++m) _Pragma("unroll") for (int k = 0; k < 2; ++k) dst[m][k] = *(const PG8_LAS bf16x8*)(lds + PG8_SA(b, h) + aoff + m * 2048 + k * 1024); } while (0)
; #define PG8_LDB(dst, b, h) do { _Pragma("unroll") for (int n = 0; n < 2; ++n) _Pragma("unroll") for (int k = 0; k < 2; ++k) dst[n][k] = *(const PG8_LAS bf16x8*)(lds + PG8_SB(b, h) + boff + n * 2048 + k * 1024); } while (0)
; #define PG8_MMA(ai, bj, At, Bt) do { __builtin_amdgcn_s_setprio(1); _Pragma("unroll") for (int m = 0; m < 4; ++m) _Pragma("unroll") for (int n = 0; n < 2; ++n) _Pragma("unroll") for (int k = 0; k < 2; ++k) \
;         acc[ai][bj][m][n] = __builtin_amdgcn_mfma_f32_16x16x32_bf16(Bt[n][k], At[m][k], acc[ai][bj][m][n], 0, 0, 0); __builtin_amdgcn_s_setprio(0); } while (0)
; #define PG8_WAIT_V(n) asm volatile("s_waitcnt vmcnt(" #n ")" ::: "memory")
; #define PG8_WAIT_L(n) asm volatile("s_waitcnt lgkmcnt(" #n ")" ::: "memory")
; #define PG8_BAR __builtin_amdgcn_s_barrier()
; #define PG8_SCHED __builtin_amdgcn_sched_barrier(0)
; template <class Epi, class Sched, bool ALIGN_EPI = false, bool SP2 = false>
; __device__ __forceinline__ void gemm_phase(PG8_LAS unsigned char* lds, const Gemm g, const Sched& S, const Epi& E) {
;     ...
;             PG8_LDB(B0, 1, 0); PG8_LDB(B1, 1, 1); PG8_SCHED; PG8_LDA(At, 1, 0); PG8_STAGE(PG8_SA(0, 1), a2 + hstep, voffA);
;             PG8_WAIT_V(8); PG8_WAIT_L(0); PG8_BAR; PG8_MMA(0, 0, At, B0); PG8_MMA(0, 1, At, B1); PG8_BAR; PG8_SCHED;
;             PG8_LDA(At, 1, 1); PG8_STAGE(PG8_SB(1, 0), b3, voffB); PG8_STAGE(PG8_SB(1, 1), b3 + hstep, voffB); PG8_STAGE(PG8_SA(1, 0), a3, voffA);
;             PG8_WAIT_V(8); PG8_WAIT_L(0); PG8_BAR; PG8_MMA(1, 0, At, B0); PG8_MMA(1, 1, At, B1); PG8_BAR; PG8_SCHED;
	s_add_i32 s18, s18, s56
	v_lshl_add_u64 v[206:207], v[206:207], 0, s[24:25]
	s_mov_b32 m0, s18
	ds_read_b128 v[178:181], v149 offset:49152
	ds_read_b128 v[182:185], v149 offset:50176
	ds_read_b128 v[186:189], v149 offset:51200
	ds_read_b128 v[190:193], v149 offset:52224
	ds_read_b128 v[194:197], v149 offset:53248
	ds_read_b128 v[198:201], v149 offset:54272
	ds_read_b128 v[202:205], v149 offset:55296
	ds_read_b128 v[212:215], v149 offset:56320
	global_load_lds_dwordx4 v[206:207], off
	s_add_i32 m0, s18, 0x2000
	s_add_u32 s50, s50, 0x40080
	v_lshl_add_u64 v[206:207], v[218:219], 0, s[24:25]
	s_addc_u32 s51, s51, 0
	s_add_i32 s18, s19, s56
	global_load_lds_dwordx4 v[206:207], off
	v_lshl_add_u64 v[206:207], s[50:51], 0, v[130:131]
	s_mov_b32 m0, s18
	s_nop 0
	global_load_lds_dwordx4 v[206:207], off
	v_lshl_add_u64 v[206:207], s[50:51], 0, v[134:135]
	s_add_i32 m0, s18, 0x2000
	s_nop 0
	global_load_lds_dwordx4 v[206:207], off
	v_lshl_add_u64 v[206:207], v[220:221], 0, s[24:25]
	s_mov_b32 m0, s61
	s_nop 0
	global_load_lds_dwordx4 v[206:207], off
	v_lshl_add_u64 v[206:207], v[222:223], 0, s[24:25]
	s_mov_b32 m0, s62
	s_nop 0
	global_load_lds_dwordx4 v[206:207], off
	s_waitcnt vmcnt(8)
	s_waitcnt lgkmcnt(0)
	s_setprio 1
	s_barrier
	v_mfma_f32_16x16x32_bf16 v[60:63], v[142:145], v[178:181], v[60:63]
	v_mfma_f32_16x16x32_bf16 v[56:59], v[154:157], v[178:181], v[56:59]
	v_mfma_f32_16x16x32_bf16 v[44:47], v[142:145], v[186:189], v[44:47]
	v_mfma_f32_16x16x32_bf16 v[40:43], v[154:157], v[186:189], v[40:43]
	v_mfma_f32_16x16x32_bf16 v[28:31], v[142:145], v[194:197], v[28:31]
	v_mfma_f32_16x16x32_bf16 v[24:27], v[154:157], v[194:197], v[24:27]
	v_mfma_f32_16x16x32_bf16 v[12:15], v[142:145], v[202:205], v[12:15]
	v_mfma_f32_16x16x32_bf16 v[8:11], v[154:157], v[202:205], v[8:11]
	v_mfma_f32_16x16x32_bf16 v[60:63], v[150:153], v[182:185], v[60:63]
	v_mfma_f32_16x16x32_bf16 v[56:59], v[158:161], v[182:185], v[56:59]
	v_mfma_f32_16x16x32_bf16 v[44:47], v[150:153], v[190:193], v[44:47]
	v_mfma_f32_16x16x32_bf16 v[40:43], v[158:161], v[190:193], v[40:43]
	v_mfma_f32_16x16x32_bf16 v[28:31], v[150:153], v[198:201], v[28:31]
	v_mfma_f32_16x16x32_bf16 v[24:27], v[158:161], v[198:201], v[24:27]
	v_mfma_f32_16x16x32_bf16 v[12:15], v[150:153], v[212:215], v[12:15]
	v_mfma_f32_16x16x32_bf16 v[8:11], v[158:161], v[212:215], v[8:11]
	s_setprio 0
	s_setprio 1
	v_mfma_f32_16x16x32_bf16 v[52:55], v[162:165], v[178:181], v[52:55]
	v_mfma_f32_16x16x32_bf16 v[48:51], v[170:173], v[178:181], v[48:51]
	v_mfma_f32_16x16x32_bf16 v[36:39], v[162:165], v[186:189], v[36:39]
	v_mfma_f32_16x16x32_bf16 v[32:35], v[170:173], v[186:189], v[32:35]
	v_mfma_f32_16x16x32_bf16 v[20:23], v[162:165], v[194:197], v[20:23]
	v_mfma_f32_16x16x32_bf16 v[16:19], v[170:173], v[194:197], v[16:19]
	v_mfma_f32_16x16x32_bf16 v[4:7], v[162:165], v[202:205], v[4:7]
	v_mfma_f32_16x16x32_bf16 v[0:3], v[170:173], v[202:205], v[0:3]
	v_mfma_f32_16x16x32_bf16 v[52:55], v[166:169], v[182:185], v[52:55]
	v_mfma_f32_16x16x32_bf16 v[48:51], v[174:177], v[182:185], v[48:51]
	v_mfma_f32_16x16x32_bf16 v[36:39], v[166:169], v[190:193], v[36:39]
	v_mfma_f32_16x16x32_bf16 v[32:35], v[174:177], v[190:193], v[32:35]
	v_mfma_f32_16x16x32_bf16 v[20:23], v[166:169], v[198:201], v[20:23]
	v_mfma_f32_16x16x32_bf16 v[16:19], v[174:177], v[198:201], v[16:19]
	v_mfma_f32_16x16x32_bf16 v[4:7], v[166:169], v[212:215], v[4:7]
	v_mfma_f32_16x16x32_bf16 v[0:3], v[174:177], v[212:215], v[0:3]
	s_setprio 0
	s_barrier
	s_add_i32 s66, s66, 2
	s_add_u32 s48, s48, 0x100
	s_addc_u32 s49, s49, 0
	s_add_u32 s47, s47, 0x100
	s_addc_u32 s65, s65, 0
	s_cmp_gt_u32 s66, 13
	s_cbranch_scc0 .LBB0_190
	s_and_b64 vcc, exec, s[6:7]
	s_cbranch_vccz .LBB0_193
	s_barrier

; #define PG8_STAGE(bufoff, gbase, voff) do { _Pragma("unroll") for (int _i = 0; _i < 2; ++_i) \
;         __builtin_amdgcn_global_load_lds((const unsigned*)((const char*)(gbase) + (voff)[_i]), (PG8_LAS unsigned*)(lds + (bufoff) + ldsw + _i * 8192), 16, 0, 0); } while (0)
; #define PG8_LDA(dst, b, h) do { _Pragma("unroll") for (int m = 0; m < 4; ++m) _Pragma("unroll") for (int k = 0; k < 2; ++k) dst[m][k] = *(const PG8_LAS bf16x8*)(lds + PG8_SA(b, h) + aoff + m * 2048 + k * 1024); } while (0)
; #define PG8_LDB(dst, b, h) do { _Pragma("unroll") for (int n = 0; n < 2; ++n) _Pragma("unroll") for (int k = 0; k < 2; ++k) dst[n][k] = *(const PG8_LAS bf16x8*)(lds + PG8_SB(b, h) + boff + n * 2048 + k * 1024); } while (0)
; #define PG8_WAIT_V(n) asm volatile("s_waitcnt vmcnt(" #n ")" ::: "memory")
; #define PG8_WAIT_L(n) asm volatile("s_waitcnt lgkmcnt(" #n ")" ::: "memory")
; #define PG8_BAR __builtin_amdgcn_s_barrier()
; #define PG8_SCHED __builtin_amdgcn_sched_barrier(0)
; template <class Epi, class Sched, bool ALIGN_EPI = false, bool SP2 = false>
; __device__ __forceinline__ void gemm_phase(PG8_LAS unsigned char* lds, const Gemm g, const Sched& S, const Epi& E) {
;     ...
;         const char* nA = has_next ? (const char*)g.A + S.a_byte(nxt, K) : cA; const char* nB = has_next ? (const char*)g.Bt + (size_t)nxt.pn * tstep : cB;
;         for (int t = 0; t < nt; t += 2) {
;             const bool last = (t == nt - 2);
;             const char* a1 = cA + (size_t)(t + 1) * kstep;
;             const char* a2 = last ? nA : cA + (size_t)(t + 2) * kstep; const char* b2 = last ? nB : cB + (size_t)(t + 2) * kstep;
;             const char* a3 = a2 + kstep; const char* b3 = b2 + kstep;
;             if (last && has_next) S.a_ready(nxt);
;             if constexpr (SP2) {
;             PG8_LDB(B0, 0, 0); PG8_LDB(B1, 0, 1); PG8_SCHED; PG8_LDA(At, 0, 0); PG8_STAGE(PG8_SA(1, 1), a1 + hstep, voffA);
;             PG8_WAIT_V(8); PG8_WAIT_L(0); PG8_BAR; PG8_MMA(0, 0, At, B0); PG8_MMA(0, 1, At, B1); PG8_BAR; PG8_SCHED;
;             PG8_LDA(At, 0, 1); PG8_STAGE(PG8_SB(0, 0), b2, voffB); PG8_STAGE(PG8_SB(0, 1), b2 + hstep, voffB); PG8_STAGE(PG8_SA(0, 0), a2, voffA);
;             PG8_WAIT_V(8); PG8_WAIT_L(0); PG8_BAR; PG8_MMA(1, 0, At, B0); PG8_MMA(1, 1, At, B1); PG8_BAR; PG8_SCHED;
.LBB0_288:
	s_add_u32 s6, s4, 0xfffc0080
	s_addc_u32 s7, s5, -1
	s_add_i32 s18, 0, 0x10000
	s_cmp_eq_u32 vcc_lo, 12
	s_cselect_b32 s77, s73, s7
	s_cselect_b32 s76, s72, s6
	s_cselect_b32 s7, s9, s79
	s_cselect_b32 s6, s71, s78
	s_add_i32 vcc_hi, 0, 0x14000
	v_add_u32_e32 v76, s18, v196
	v_add_u32_e32 v100, vcc_hi, v196
	ds_read_b128 v[64:67], v76
	ds_read_b128 v[68:71], v76 offset:1024
	ds_read_b128 v[72:75], v76 offset:2048
	ds_read_b128 v[76:79], v76 offset:3072
	ds_read_b128 v[88:91], v100
	ds_read_b128 v[92:95], v100 offset:1024
	ds_read_b128 v[96:99], v100 offset:2048
	ds_read_b128 v[100:103], v100 offset:3072
	v_lshl_add_u64 v[164:165], s[4:5], 0, v[178:179]
	s_add_i32 m0, s91, 0xc000
	ds_read_b128 v[160:163], v218
	ds_read_b128 v[182:185], v218 offset:1024
	ds_read_b128 v[186:189], v218 offset:2048
	ds_read_b128 v[190:193], v218 offset:3072
	ds_read_b128 v[212:215], v218 offset:4096
	ds_read_b128 v[220:223], v218 offset:5120
	ds_read_b128 v[224:227], v218 offset:6144
	ds_read_b128 v[228:231], v218 offset:7168
	global_load_lds_dwordx4 v[164:165], off
	v_lshl_add_u64 v[164:165], s[4:5], 0, v[180:181]
	s_add_i32 m0, s91, 0xe000
	s_nop 0
	global_load_lds_dwordx4 v[164:165], off
	s_waitcnt vmcnt(8)
	s_waitcnt lgkmcnt(0)
	s_setprio 1
	s_barrier
	v_mfma_f32_16x16x32_bf16 v[156:159], v[64:67], v[160:163], v[156:159]
	v_mfma_f32_16x16x32_bf16 v[152:155], v[72:75], v[160:163], v[152:155]
	v_mfma_f32_16x16x32_bf16 v[140:143], v[64:67], v[186:189], v[140:143]
	v_mfma_f32_16x16x32_bf16 v[136:139], v[72:75], v[186:189], v[136:139]
	v_mfma_f32_16x16x32_bf16 v[124:127], v[64:67], v[212:215], v[124:127]
	v_mfma_f32_16x16x32_bf16 v[120:123], v[72:75], v[212:215], v[120:123]
	v_mfma_f32_16x16x32_bf16 v[108:111], v[64:67], v[224:227], v[108:111]
	v_mfma_f32_16x16x32_bf16 v[104:107], v[72:75], v[224:227], v[104:107]
	v_mfma_f32_16x16x32_bf16 v[156:159], v[68:71], v[182:185], v[156:159]
	v_mfma_f32_16x16x32_bf16 v[152:155], v[76:79], v[182:185], v[152:155]
	v_mfma_f32_16x16x32_bf16 v[140:143], v[68:71], v[190:193], v[140:143]
	v_mfma_f32_16x16x32_bf16 v[136:139], v[76:79], v[190:193], v[136:139]
	v_mfma_f32_16x16x32_bf16 v[124:127], v[68:71], v[220:223], v[124:127]
	v_mfma_f32_16x16x32_bf16 v[120:123], v[76:79], v[220:223], v[120:123]
	v_mfma_f32_16x16x32_bf16 v[108:111], v[68:71], v[228:231], v[108:111]
	v_mfma_f32_16x16x32_bf16 v[104:107], v[76:79], v[228:231], v[104:107]
	s_setprio 0
	s_setprio 1
	v_mfma_f32_16x16x32_bf16 v[148:151], v[88:91], v[160:163], v[148:151]
	v_mfma_f32_16x16x32_bf16 v[144:147], v[96:99], v[160:163], v[144:147]
	v_mfma_f32_16x16x32_bf16 v[132:135], v[88:91], v[186:189], v[132:135]
	v_mfma_f32_16x16x32_bf16 v[128:131], v[96:99], v[186:189], v[128:131]
	v_mfma_f32_16x16x32_bf16 v[116:119], v[88:91], v[212:215], v[116:119]
	v_mfma_f32_16x16x32_bf16 v[112:115], v[96:99], v[212:215], v[112:115]
	v_mfma_f32_16x16x32_bf16 v[84:87], v[88:91], v[224:227], v[84:87]
	v_mfma_f32_16x16x32_bf16 v[80:83], v[96:99], v[224:227], v[80:83]
	v_mfma_f32_16x16x32_bf16 v[148:151], v[92:95], v[182:185], v[148:151]
	v_mfma_f32_16x16x32_bf16 v[144:147], v[100:103], v[182:185], v[144:147]
	v_mfma_f32_16x16x32_bf16 v[132:135], v[92:95], v[190:193], v[132:135]
	v_mfma_f32_16x16x32_bf16 v[128:131], v[100:103], v[190:193], v[128:131]
	v_mfma_f32_16x16x32_bf16 v[116:119], v[92:95], v[220:223], v[116:119]
	v_mfma_f32_16x16x32_bf16 v[112:115], v[100:103], v[220:223], v[112:115]
	v_mfma_f32_16x16x32_bf16 v[84:87], v[92:95], v[228:231], v[84:87]
	v_mfma_f32_16x16x32_bf16 v[80:83], v[100:103], v[228:231], v[80:83]
	s_setprio 0
	s_barrier
	s_add_i32 s18, s18, s85
	v_lshl_add_u64 v[164:165], s[6:7], 0, v[208:209]
	s_mov_b32 m0, s18
	ds_read_b128 v[160:163], v218 offset:16384
	ds_read_b128 v[182:185], v218 offset:17408
	ds_read_b128 v[186:189], v218 offset:18432
	ds_read_b128 v[190:193], v218 offset:19456
	ds_read_b128 v[212:215], v218 offset:20480
	ds_read_b128 v[220:223], v218 offset:21504
	ds_read_b128 v[224:227], v218 offset:22528
	ds_read_b128 v[228:231], v218 offset:23552
	global_load_lds_dwordx4 v[164:165], off
	s_add_i32 m0, s18, 0x2000
	s_add_u32 s18, s6, 0x40000
	v_lshl_add_u64 v[194:195], s[6:7], 0, v[170:171]
	s_addc_u32 s19, s7, 0
	s_add_i32 vcc_hi, vcc_hi, s85
	global_load_lds_dwordx4 v[194:195], off
	v_lshl_add_u64 v[232:233], s[18:19], 0, v[208:209]
	s_mov_b32 m0, vcc_hi
	v_lshl_add_u64 v[234:235], s[76:77], 0, v[168:169]
	global_load_lds_dwordx4 v[232:233], off
	v_lshl_add_u64 v[232:233], s[18:19], 0, v[170:171]
	s_add_i32 m0, vcc_hi, 0x2000
	s_nop 0
	global_load_lds_dwordx4 v[232:233], off
	v_lshl_add_u64 v[232:233], s[76:77], 0, v[166:167]
	s_mov_b32 m0, s91
	s_nop 0
	global_load_lds_dwordx4 v[232:233], off
	s_mov_b32 m0, s92
	s_nop 0
	global_load_lds_dwordx4 v[234:235], off
	s_waitcnt vmcnt(8)
	s_waitcnt lgkmcnt(0)
	s_setprio 1
	s_barrier
; #define PG8_STAGE(bufoff, gbase, voff) do { _Pragma("unroll") for (int _i = 0; _i < 2; ++_i) \
;         __builtin_amdgcn_global_load_lds((const unsigned*)((const char*)(gbase) + (voff)[_i]), (PG8_LAS unsigned*)(lds + (bufoff) + ldsw + _i * 8192), 16, 0, 0); } while (0)
; #define PG8_LDA(dst, b, h) do { _Pragma("unroll") for (int m = 0; m < 4; ++m) _Pragma("unroll") for (int k = 0; k < 2; ++k) dst[m][k] = *(const PG8_LAS bf16x8*)(lds + PG8_SA(b, h) + aoff + m * 2048 + k * 1024); } while (0)
; #define PG8_LDB(dst, b, h) do { _Pragma("unroll") for (int n = 0; n < 2; ++n) _Pragma("unroll") for (int k = 0; k < 2; ++k) dst[n][k] = *(const PG8_LAS bf16x8*)(lds + PG8_SB(b, h) + boff + n * 2048 + k * 1024); } while (0)
; #define PG8_MMA(ai, bj, At, Bt) do { __builtin_amdgcn_s_setprio(1); _Pragma("unroll") for (int m = 0; m < 4; ++m) _Pragma("unroll") for (int n = 0; n < 2; ++n) _Pragma("unroll") for (int k = 0; k < 2; ++k) \
;         acc[ai][bj][m][n] = __builtin_amdgcn_mfma_f32_16x16x32_bf16(Bt[n][k], At[m][k], acc[ai][bj][m][n], 0, 0, 0); __builtin_amdgcn_s_setprio(0); } while (0)
; #define PG8_WAIT_V(n) asm volatile("s_waitcnt vmcnt(" #n ")" ::: "memory")
; #define PG8_WAIT_L(n) asm volatile("s_waitcnt lgkmcnt(" #n ")" ::: "memory")
; #define PG8_BAR __builtin_amdgcn_s_barrier()
; #define PG8_SCHED __builtin_amdgcn_sched_barrier(0)
; template <class Epi, class Sched, bool ALIGN_EPI = false, bool SP2 = false>
; __device__ __forceinline__ void gemm_phase(PG8_LAS unsigned char* lds, const Gemm g, const Sched& S, const Epi& E) {
;     ...
;             PG8_LDA(At, 0, 1); PG8_STAGE(PG8_SB(0, 0), b2, voffB); PG8_STAGE(PG8_SB(0, 1), b2 + hstep, voffB); PG8_STAGE(PG8_SA(0, 0), a2, voffA);
;             PG8_WAIT_V(8); PG8_WAIT_L(0); PG8_BAR; PG8_MMA(1, 0, At, B0); PG8_MMA(1, 1, At, B1); PG8_BAR; PG8_SCHED;
;             PG8_LDB(B0, 1, 0); PG8_LDB(B1, 1, 1); PG8_SCHED; PG8_LDA(At, 1, 0); PG8_STAGE(PG8_SA(0, 1), a2 + hstep, voffA);
;             PG8_WAIT_V(8); PG8_WAIT_L(0); PG8_BAR; PG8_MMA(0, 0, At, B0); PG8_MMA(0, 1, At, B1); PG8_BAR; PG8_SCHED;
	v_mfma_f32_16x16x32_bf16 v[60:63], v[64:67], v[160:163], v[60:63]
	v_mfma_f32_16x16x32_bf16 v[56:59], v[72:75], v[160:163], v[56:59]
	v_mfma_f32_16x16x32_bf16 v[44:47], v[64:67], v[186:189], v[44:47]
	v_mfma_f32_16x16x32_bf16 v[40:43], v[72:75], v[186:189], v[40:43]
	v_mfma_f32_16x16x32_bf16 v[28:31], v[64:67], v[212:215], v[28:31]
	v_mfma_f32_16x16x32_bf16 v[24:27], v[72:75], v[212:215], v[24:27]
	v_mfma_f32_16x16x32_bf16 v[12:15], v[64:67], v[224:227], v[12:15]
	v_mfma_f32_16x16x32_bf16 v[8:11], v[72:75], v[224:227], v[8:11]
	v_mfma_f32_16x16x32_bf16 v[60:63], v[68:71], v[182:185], v[60:63]
	v_mfma_f32_16x16x32_bf16 v[56:59], v[76:79], v[182:185], v[56:59]
	v_mfma_f32_16x16x32_bf16 v[44:47], v[68:71], v[190:193], v[44:47]
	v_mfma_f32_16x16x32_bf16 v[40:43], v[76:79], v[190:193], v[40:43]
	v_mfma_f32_16x16x32_bf16 v[28:31], v[68:71], v[220:223], v[28:31]
	v_mfma_f32_16x16x32_bf16 v[24:27], v[76:79], v[220:223], v[24:27]
	v_mfma_f32_16x16x32_bf16 v[12:15], v[68:71], v[228:231], v[12:15]
	v_mfma_f32_16x16x32_bf16 v[8:11], v[76:79], v[228:231], v[8:11]
	s_setprio 0
	s_setprio 1
	v_mfma_f32_16x16x32_bf16 v[52:55], v[88:91], v[160:163], v[52:55]
	v_mfma_f32_16x16x32_bf16 v[48:51], v[96:99], v[160:163], v[48:51]
	v_mfma_f32_16x16x32_bf16 v[36:39], v[88:91], v[186:189], v[36:39]
	v_mfma_f32_16x16x32_bf16 v[32:35], v[96:99], v[186:189], v[32:35]
	v_mfma_f32_16x16x32_bf16 v[20:23], v[88:91], v[212:215], v[20:23]
	v_mfma_f32_16x16x32_bf16 v[16:19], v[96:99], v[212:215], v[16:19]
	v_mfma_f32_16x16x32_bf16 v[4:7], v[88:91], v[224:227], v[4:7]
	v_mfma_f32_16x16x32_bf16 v[0:3], v[96:99], v[224:227], v[0:3]
	v_mfma_f32_16x16x32_bf16 v[52:55], v[92:95], v[182:185], v[52:55]
	v_mfma_f32_16x16x32_bf16 v[48:51], v[100:103], v[182:185], v[48:51]
	v_mfma_f32_16x16x32_bf16 v[36:39], v[92:95], v[190:193], v[36:39]
	v_mfma_f32_16x16x32_bf16 v[32:35], v[100:103], v[190:193], v[32:35]
	v_mfma_f32_16x16x32_bf16 v[20:23], v[92:95], v[220:223], v[20:23]
	v_mfma_f32_16x16x32_bf16 v[16:19], v[100:103], v[220:223], v[16:19]
	v_mfma_f32_16x16x32_bf16 v[4:7], v[92:95], v[228:231], v[4:7]
	v_mfma_f32_16x16x32_bf16 v[0:3], v[100:103], v[228:231], v[0:3]
	s_setprio 0
	s_barrier
	s_add_i32 vcc_hi, 0, 0x18000
	s_add_i32 s34, 0, 0x1c000
	v_add_u32_e32 v76, vcc_hi, v196
	v_add_u32_e32 v100, s34, v196
	ds_read_b128 v[64:67], v76
	ds_read_b128 v[68:71], v76 offset:1024
	ds_read_b128 v[72:75], v76 offset:2048
	ds_read_b128 v[76:79], v76 offset:3072
	ds_read_b128 v[88:91], v100
	ds_read_b128 v[92:95], v100 offset:1024
	ds_read_b128 v[96:99], v100 offset:2048
	ds_read_b128 v[100:103], v100 offset:3072
	s_add_u32 s18, s76, 0x40000
	s_addc_u32 s19, s77, 0
	s_mov_b32 m0, s93
	v_lshl_add_u64 v[236:237], s[18:19], 0, v[166:167]
	ds_read_b128 v[160:163], v218 offset:32768
	ds_read_b128 v[182:185], v218 offset:33792
	ds_read_b128 v[186:189], v218 offset:34816
	ds_read_b128 v[190:193], v218 offset:35840
	ds_read_b128 v[212:215], v218 offset:36864
	ds_read_b128 v[220:223], v218 offset:37888
	ds_read_b128 v[224:227], v218 offset:38912
	ds_read_b128 v[228:231], v218 offset:39936
	global_load_lds_dwordx4 v[236:237], off
	v_lshl_add_u64 v[236:237], s[18:19], 0, v[168:169]
	s_mov_b32 m0, s94
	s_nop 0
	global_load_lds_dwordx4 v[236:237], off
	s_waitcnt vmcnt(8)
	s_waitcnt lgkmcnt(0)
	s_setprio 1
	s_barrier
	v_mfma_f32_16x16x32_bf16 v[156:159], v[64:67], v[160:163], v[156:159]
	v_mfma_f32_16x16x32_bf16 v[152:155], v[72:75], v[160:163], v[152:155]
	v_mfma_f32_16x16x32_bf16 v[140:143], v[64:67], v[186:189], v[140:143]
	v_mfma_f32_16x16x32_bf16 v[136:139], v[72:75], v[186:189], v[136:139]
	v_mfma_f32_16x16x32_bf16 v[124:127], v[64:67], v[212:215], v[124:127]
	v_mfma_f32_16x16x32_bf16 v[120:123], v[72:75], v[212:215], v[120:123]
	v_mfma_f32_16x16x32_bf16 v[108:111], v[64:67], v[224:227], v[108:111]
	v_mfma_f32_16x16x32_bf16 v[104:107], v[72:75], v[224:227], v[104:107]
	v_mfma_f32_16x16x32_bf16 v[156:159], v[68:71], v[182:185], v[156:159]
	v_mfma_f32_16x16x32_bf16 v[152:155], v[76:79], v[182:185], v[152:155]
	v_mfma_f32_16x16x32_bf16 v[140:143], v[68:71], v[190:193], v[140:143]
	v_mfma_f32_16x16x32_bf16 v[136:139], v[76:79], v[190:193], v[136:139]
	v_mfma_f32_16x16x32_bf16 v[124:127], v[68:71], v[220:223], v[124:127]
	v_mfma_f32_16x16x32_bf16 v[120:123], v[76:79], v[220:223], v[120:123]
	v_mfma_f32_16x16x32_bf16 v[108:111], v[68:71], v[228:231], v[108:111]
	v_mfma_f32_16x16x32_bf16 v[104:107], v[76:79], v[228:231], v[104:107]
	s_setprio 0
	s_setprio 1
	v_mfma_f32_16x16x32_bf16 v[148:151], v[88:91], v[160:163], v[148:151]
	v_mfma_f32_16x16x32_bf16 v[144:147], v[96:99], v[160:163], v[144:147]
	v_mfma_f32_16x16x32_bf16 v[132:135], v[88:91], v[186:189], v[132:135]
	v_mfma_f32_16x16x32_bf16 v[128:131], v[96:99], v[186:189], v[128:131]
	v_mfma_f32_16x16x32_bf16 v[116:119], v[88:91], v[212:215], v[116:119]
	v_mfma_f32_16x16x32_bf16 v[112:115], v[96:99], v[212:215], v[112:115]
	v_mfma_f32_16x16x32_bf16 v[84:87], v[88:91], v[224:227], v[84:87]
	v_mfma_f32_16x16x32_bf16 v[80:83], v[96:99], v[224:227], v[80:83]
	v_mfma_f32_16x16x32_bf16 v[148:151], v[92:95], v[182:185], v[148:151]
	v_mfma_f32_16x16x32_bf16 v[144:147], v[100:103], v[182:185], v[144:147]
	v_mfma_f32_16x16x32_bf16 v[132:135], v[92:95], v[190:193], v[132:135]
	v_mfma_f32_16x16x32_bf16 v[128:131], v[100:103], v[190:193], v[128:131]
	v_mfma_f32_16x16x32_bf16 v[116:119], v[92:95], v[220:223], v[116:119]
	v_mfma_f32_16x16x32_bf16 v[112:115], v[100:103], v[220:223], v[112:115]
	v_mfma_f32_16x16x32_bf16 v[84:87], v[92:95], v[228:231], v[84:87]
	v_mfma_f32_16x16x32_bf16 v[80:83], v[100:103], v[228:231], v[80:83]
	s_setprio 0
	s_barrier
; #define PG8_STAGE(bufoff, gbase, voff) do { _Pragma("unroll") for (int _i = 0; _i < 2; ++_i) \
;         __builtin_amdgcn_global_load_lds((const unsigned*)((const char*)(gbase) + (voff)[_i]), (PG8_LAS unsigned*)(lds + (bufoff) + ldsw + _i * 8192), 16, 0, 0); } while (0)
; #define PG8_LDA(dst, b, h) do { _Pragma("unroll") for (int m = 0; m < 4; ++m) _Pragma("unroll") for (int k = 0; k < 2; ++k) dst[m][k] = *(const PG8_LAS bf16x8*)(lds + PG8_SA(b, h) + aoff + m * 2048 + k * 1024); } while (0)
; #define PG8_LDB(dst, b, h) do { _Pragma("unroll") for (int n = 0; n < 2; ++n) _Pragma("unroll") for (int k = 0; k < 2; ++k) dst[n][k] = *(const PG8_LAS bf16x8*)(lds + PG8_SB(b, h) + boff + n * 2048 + k * 1024); } while (0)
; #define PG8_MMA(ai, bj, At, Bt) do { __builtin_amdgcn_s_setprio(1); _Pragma("unroll") for (int m = 0; m < 4; ++m) _Pragma("unroll") for (int n = 0; n < 2; ++n) _Pragma("unroll") for (int k = 0; k < 2; ++k) \
;         acc[ai][bj][m][n] = __builtin_amdgcn_mfma_f32_16x16x32_bf16(Bt[n][k], At[m][k], acc[ai][bj][m][n], 0, 0, 0); __builtin_amdgcn_s_setprio(0); } while (0)
; #define PG8_WAIT_V(n) asm volatile("s_waitcnt vmcnt(" #n ")" ::: "memory")
; #define PG8_WAIT_L(n) asm volatile("s_waitcnt lgkmcnt(" #n ")" ::: "memory")
; #define PG8_BAR __builtin_amdgcn_s_barrier()
; #define PG8_SCHED __builtin_amdgcn_sched_barrier(0)
; template <class Epi, class Sched, bool ALIGN_EPI = false, bool SP2 = false>
; __device__ __forceinline__ void gemm_phase(PG8_LAS unsigned char* lds, const Gemm g, const Sched& S, const Epi& E) {
;     ...
;             PG8_LDB(B0, 1, 0); PG8_LDB(B1, 1, 1); PG8_SCHED; PG8_LDA(At, 1, 0); PG8_STAGE(PG8_SA(0, 1), a2 + hstep, voffA);
;             PG8_WAIT_V(8); PG8_WAIT_L(0); PG8_BAR; PG8_MMA(0, 0, At, B0); PG8_MMA(0, 1, At, B1); PG8_BAR; PG8_SCHED;
;             PG8_LDA(At, 1, 1); PG8_STAGE(PG8_SB(1, 0), b3, voffB); PG8_STAGE(PG8_SB(1, 1), b3 + hstep, voffB); PG8_STAGE(PG8_SA(1, 0), a3, voffA);
;             PG8_WAIT_V(8); PG8_WAIT_L(0); PG8_BAR; PG8_MMA(1, 0, At, B0); PG8_MMA(1, 1, At, B1); PG8_BAR; PG8_SCHED;
	s_add_i32 s18, vcc_hi, s85
	v_lshl_add_u64 v[164:165], v[164:165], 0, s[24:25]
	s_mov_b32 m0, s18
	ds_read_b128 v[160:163], v218 offset:49152
	ds_read_b128 v[182:185], v218 offset:50176
	ds_read_b128 v[186:189], v218 offset:51200
	ds_read_b128 v[190:193], v218 offset:52224
	ds_read_b128 v[212:215], v218 offset:53248
	ds_read_b128 v[220:223], v218 offset:54272
	ds_read_b128 v[224:227], v218 offset:55296
	ds_read_b128 v[228:231], v218 offset:56320
	global_load_lds_dwordx4 v[164:165], off
	s_add_i32 m0, s18, 0x2000
	s_add_u32 s6, s6, 0x40080
	v_lshl_add_u64 v[164:165], v[194:195], 0, s[24:25]
	s_addc_u32 s7, s7, 0
	s_add_i32 s18, s34, s85
	global_load_lds_dwordx4 v[164:165], off
	v_lshl_add_u64 v[164:165], s[6:7], 0, v[208:209]
	s_mov_b32 m0, s18
	s_nop 0
	global_load_lds_dwordx4 v[164:165], off
	v_lshl_add_u64 v[164:165], s[6:7], 0, v[170:171]
	s_add_i32 m0, s18, 0x2000
	s_nop 0
	global_load_lds_dwordx4 v[164:165], off
	v_lshl_add_u64 v[164:165], v[232:233], 0, s[24:25]
	s_mov_b32 m0, s95
	s_nop 0
	global_load_lds_dwordx4 v[164:165], off
	v_lshl_add_u64 v[164:165], v[234:235], 0, s[24:25]
	s_mov_b32 m0, s96
	s_nop 0
	global_load_lds_dwordx4 v[164:165], off
	s_waitcnt vmcnt(8)
	s_waitcnt lgkmcnt(0)
	s_setprio 1
	s_barrier
	v_mfma_f32_16x16x32_bf16 v[60:63], v[64:67], v[160:163], v[60:63]
	v_mfma_f32_16x16x32_bf16 v[56:59], v[72:75], v[160:163], v[56:59]
	v_mfma_f32_16x16x32_bf16 v[44:47], v[64:67], v[186:189], v[44:47]
	v_mfma_f32_16x16x32_bf16 v[40:43], v[72:75], v[186:189], v[40:43]
	v_mfma_f32_16x16x32_bf16 v[28:31], v[64:67], v[212:215], v[28:31]
	v_mfma_f32_16x16x32_bf16 v[24:27], v[72:75], v[212:215], v[24:27]
	v_mfma_f32_16x16x32_bf16 v[12:15], v[64:67], v[224:227], v[12:15]
	v_mfma_f32_16x16x32_bf16 v[8:11], v[72:75], v[224:227], v[8:11]
	v_mfma_f32_16x16x32_bf16 v[60:63], v[68:71], v[182:185], v[60:63]
	v_mfma_f32_16x16x32_bf16 v[56:59], v[76:79], v[182:185], v[56:59]
	v_mfma_f32_16x16x32_bf16 v[44:47], v[68:71], v[190:193], v[44:47]
	v_mfma_f32_16x16x32_bf16 v[40:43], v[76:79], v[190:193], v[40:43]
	v_mfma_f32_16x16x32_bf16 v[28:31], v[68:71], v[220:223], v[28:31]
	v_mfma_f32_16x16x32_bf16 v[24:27], v[76:79], v[220:223], v[24:27]
	v_mfma_f32_16x16x32_bf16 v[12:15], v[68:71], v[228:231], v[12:15]
	v_mfma_f32_16x16x32_bf16 v[8:11], v[76:79], v[228:231], v[8:11]
	s_setprio 0
	s_setprio 1
	v_mfma_f32_16x16x32_bf16 v[52:55], v[88:91], v[160:163], v[52:55]
	v_mfma_f32_16x16x32_bf16 v[48:51], v[96:99], v[160:163], v[48:51]
	v_mfma_f32_16x16x32_bf16 v[36:39], v[88:91], v[186:189], v[36:39]
	v_mfma_f32_16x16x32_bf16 v[32:35], v[96:99], v[186:189], v[32:35]
	v_mfma_f32_16x16x32_bf16 v[20:23], v[88:91], v[212:215], v[20:23]
	v_mfma_f32_16x16x32_bf16 v[16:19], v[96:99], v[212:215], v[16:19]
	v_mfma_f32_16x16x32_bf16 v[4:7], v[88:91], v[224:227], v[4:7]
	v_mfma_f32_16x16x32_bf16 v[0:3], v[96:99], v[224:227], v[0:3]
	v_mfma_f32_16x16x32_bf16 v[52:55], v[92:95], v[182:185], v[52:55]
	v_mfma_f32_16x16x32_bf16 v[48:51], v[100:103], v[182:185], v[48:51]
	v_mfma_f32_16x16x32_bf16 v[36:39], v[92:95], v[190:193], v[36:39]
	v_mfma_f32_16x16x32_bf16 v[32:35], v[100:103], v[190:193], v[32:35]
	v_mfma_f32_16x16x32_bf16 v[20:23], v[92:95], v[220:223], v[20:23]
	v_mfma_f32_16x16x32_bf16 v[16:19], v[100:103], v[220:223], v[16:19]
	v_mfma_f32_16x16x32_bf16 v[4:7], v[92:95], v[228:231], v[4:7]
	v_mfma_f32_16x16x32_bf16 v[0:3], v[100:103], v[228:231], v[0:3]
	s_setprio 0
	s_barrier
	s_add_i32 vcc_lo, vcc_lo, 2
	s_add_u32 s4, s4, 0x100
	s_addc_u32 s5, s5, 0
	s_add_u32 s78, s78, 0x100
	s_addc_u32 s79, s79, 0
	s_cmp_gt_u32 vcc_lo, 13
	s_cbranch_scc0 .LBB0_288
	s_and_b64 vcc, exec, s[58:59]
	s_cbranch_vccz .LBB0_291
	s_barrier

; #define PG8_STAGE(bufoff, gbase, voff) do { _Pragma("unroll") for (int _i = 0; _i < 2; ++_i) \
;         __builtin_amdgcn_global_load_lds((const unsigned*)((const char*)(gbase) + (voff)[_i]), (PG8_LAS unsigned*)(lds + (bufoff) + ldsw + _i * 8192), 16, 0, 0); } while (0)
; #define PG8_LDA(dst, b, h) do { _Pragma("unroll") for (int m = 0; m < 4; ++m) _Pragma("unroll") for (int k = 0; k < 2; ++k) dst[m][k] = *(const PG8_LAS bf16x8*)(lds + PG8_SA(b, h) + aoff + m * 2048 + k * 1024); } while (0)
; #define PG8_LDB(dst, b, h) do { _Pragma("unroll") for (int n = 0; n < 2; ++n) _Pragma("unroll") for (int k = 0; k < 2; ++k) dst[n][k] = *(const PG8_LAS bf16x8*)(lds + PG8_SB(b, h) + boff + n * 2048 + k * 1024); } while (0)
; #define PG8_WAIT_V(n) asm volatile("s_waitcnt vmcnt(" #n ")" ::: "memory")
; #define PG8_WAIT_L(n) asm volatile("s_waitcnt lgkmcnt(" #n ")" ::: "memory")
; #define PG8_BAR __builtin_amdgcn_s_barrier()
; #define PG8_SCHED __builtin_amdgcn_sched_barrier(0)
; template <class Epi, class Sched, bool ALIGN_EPI = false, bool SP2 = false>
; __device__ __forceinline__ void gemm_phase(PG8_LAS unsigned char* lds, const Gemm g, const Sched& S, const Epi& E) {
;     ...
;         const char* nA = has_next ? (const char*)g.A + S.a_byte(nxt, K) : cA; const char* nB = has_next ? (const char*)g.Bt + (size_t)nxt.pn * tstep : cB;
;         for (int t = 0; t < nt; t += 2) {
;             const bool last = (t == nt - 2);
;             const char* a1 = cA + (size_t)(t + 1) * kstep;
;             const char* a2 = last ? nA : cA + (size_t)(t + 2) * kstep; const char* b2 = last ? nB : cB + (size_t)(t + 2) * kstep;
;             const char* a3 = a2 + kstep; const char* b3 = b2 + kstep;
;             if (last && has_next) S.a_ready(nxt);
;             if constexpr (SP2) {
;             PG8_LDB(B0, 0, 0); PG8_LDB(B1, 0, 1); PG8_SCHED; PG8_LDA(At, 0, 0); PG8_STAGE(PG8_SA(1, 1), a1 + hstep, voffA);
;             PG8_WAIT_V(8); PG8_WAIT_L(0); PG8_BAR; PG8_MMA(0, 0, At, B0); PG8_MMA(0, 1, At, B1); PG8_BAR; PG8_SCHED;
;             PG8_LDA(At, 0, 1); PG8_STAGE(PG8_SB(0, 0), b2, voffB); PG8_STAGE(PG8_SB(0, 1), b2 + hstep, voffB); PG8_STAGE(PG8_SA(0, 0), a2, voffA);
;             PG8_WAIT_V(8); PG8_WAIT_L(0); PG8_BAR; PG8_MMA(1, 0, At, B0); PG8_MMA(1, 1, At, B1); PG8_BAR; PG8_SCHED;
.LBB0_334:
	s_add_u32 s8, s6, 0xfffc0080
	s_addc_u32 s9, s7, -1
	s_add_i32 s18, 0, 0x10000
	s_cmp_eq_u32 s63, 12
	s_cselect_b32 s53, s5, s9
	s_cselect_b32 s52, s16, s8
	s_cselect_b32 s9, s38, s62
	s_cselect_b32 s8, s45, s47
	s_add_i32 s19, 0, 0x14000
	v_add_u32_e32 v158, s18, v155
	v_add_u32_e32 v174, s19, v155
	ds_read_b128 v[142:145], v158
	ds_read_b128 v[146:149], v158 offset:1024
	ds_read_b128 v[150:153], v158 offset:2048
	ds_read_b128 v[158:161], v158 offset:3072
	ds_read_b128 v[162:165], v174
	ds_read_b128 v[166:169], v174 offset:1024
	ds_read_b128 v[170:173], v174 offset:2048
	ds_read_b128 v[174:177], v174 offset:3072
	v_lshl_add_u64 v[206:207], s[6:7], 0, v[138:139]
	s_add_i32 m0, s11, 0xc000
	ds_read_b128 v[178:181], v157
	ds_read_b128 v[182:185], v157 offset:1024
	ds_read_b128 v[186:189], v157 offset:2048
	ds_read_b128 v[190:193], v157 offset:3072
	ds_read_b128 v[194:197], v157 offset:4096
	ds_read_b128 v[198:201], v157 offset:5120
	ds_read_b128 v[202:205], v157 offset:6144
	ds_read_b128 v[218:221], v157 offset:7168
	global_load_lds_dwordx4 v[206:207], off
	v_lshl_add_u64 v[206:207], s[6:7], 0, v[140:141]
	s_add_i32 m0, s11, 0xe000
	s_nop 0
	global_load_lds_dwordx4 v[206:207], off
	s_waitcnt vmcnt(8)
	s_waitcnt lgkmcnt(0)
	s_setprio 1
	s_barrier
	v_mfma_f32_16x16x32_bf16 v[124:127], v[142:145], v[178:181], v[124:127]
	v_mfma_f32_16x16x32_bf16 v[120:123], v[150:153], v[178:181], v[120:123]
	v_mfma_f32_16x16x32_bf16 v[108:111], v[142:145], v[186:189], v[108:111]
	v_mfma_f32_16x16x32_bf16 v[104:107], v[150:153], v[186:189], v[104:107]
	v_mfma_f32_16x16x32_bf16 v[92:95], v[142:145], v[194:197], v[92:95]
	v_mfma_f32_16x16x32_bf16 v[88:91], v[150:153], v[194:197], v[88:91]
	v_mfma_f32_16x16x32_bf16 v[76:79], v[142:145], v[202:205], v[76:79]
	v_mfma_f32_16x16x32_bf16 v[72:75], v[150:153], v[202:205], v[72:75]
	v_mfma_f32_16x16x32_bf16 v[124:127], v[146:149], v[182:185], v[124:127]
	v_mfma_f32_16x16x32_bf16 v[120:123], v[158:161], v[182:185], v[120:123]
	v_mfma_f32_16x16x32_bf16 v[108:111], v[146:149], v[190:193], v[108:111]
	v_mfma_f32_16x16x32_bf16 v[104:107], v[158:161], v[190:193], v[104:107]
	v_mfma_f32_16x16x32_bf16 v[92:95], v[146:149], v[198:201], v[92:95]
	v_mfma_f32_16x16x32_bf16 v[88:91], v[158:161], v[198:201], v[88:91]
	v_mfma_f32_16x16x32_bf16 v[76:79], v[146:149], v[218:221], v[76:79]
	v_mfma_f32_16x16x32_bf16 v[72:75], v[158:161], v[218:221], v[72:75]
	s_setprio 0
	s_setprio 1
	v_mfma_f32_16x16x32_bf16 v[116:119], v[162:165], v[178:181], v[116:119]
	v_mfma_f32_16x16x32_bf16 v[112:115], v[170:173], v[178:181], v[112:115]
	v_mfma_f32_16x16x32_bf16 v[100:103], v[162:165], v[186:189], v[100:103]
	v_mfma_f32_16x16x32_bf16 v[96:99], v[170:173], v[186:189], v[96:99]
	v_mfma_f32_16x16x32_bf16 v[84:87], v[162:165], v[194:197], v[84:87]
	v_mfma_f32_16x16x32_bf16 v[80:83], v[170:173], v[194:197], v[80:83]
	v_mfma_f32_16x16x32_bf16 v[68:71], v[162:165], v[202:205], v[68:71]
	v_mfma_f32_16x16x32_bf16 v[64:67], v[170:173], v[202:205], v[64:67]
	v_mfma_f32_16x16x32_bf16 v[116:119], v[166:169], v[182:185], v[116:119]
	v_mfma_f32_16x16x32_bf16 v[112:115], v[174:177], v[182:185], v[112:115]
	v_mfma_f32_16x16x32_bf16 v[100:103], v[166:169], v[190:193], v[100:103]
	v_mfma_f32_16x16x32_bf16 v[96:99], v[174:177], v[190:193], v[96:99]
	v_mfma_f32_16x16x32_bf16 v[84:87], v[166:169], v[198:201], v[84:87]
	v_mfma_f32_16x16x32_bf16 v[80:83], v[174:177], v[198:201], v[80:83]
	v_mfma_f32_16x16x32_bf16 v[68:71], v[166:169], v[218:221], v[68:71]
	v_mfma_f32_16x16x32_bf16 v[64:67], v[174:177], v[218:221], v[64:67]
	s_setprio 0
	s_barrier
	s_add_i32 s18, s18, s31
	v_lshl_add_u64 v[206:207], s[8:9], 0, v[130:131]
	s_mov_b32 m0, s18
	ds_read_b128 v[178:181], v157 offset:16384
	ds_read_b128 v[182:185], v157 offset:17408
	ds_read_b128 v[186:189], v157 offset:18432
	ds_read_b128 v[190:193], v157 offset:19456
	ds_read_b128 v[194:197], v157 offset:20480
	ds_read_b128 v[198:201], v157 offset:21504
	ds_read_b128 v[202:205], v157 offset:22528
	ds_read_b128 v[218:221], v157 offset:23552
	global_load_lds_dwordx4 v[206:207], off
	s_add_i32 m0, s18, 0x2000
	s_add_u32 s64, s8, 0x40000
	v_lshl_add_u64 v[212:213], s[8:9], 0, v[134:135]
	s_addc_u32 s65, s9, 0
	s_add_i32 s18, s19, s31
	global_load_lds_dwordx4 v[212:213], off
	v_lshl_add_u64 v[214:215], s[64:65], 0, v[130:131]
	s_mov_b32 m0, s18
	v_lshl_add_u64 v[222:223], s[52:53], 0, v[132:133]
	global_load_lds_dwordx4 v[214:215], off
	v_lshl_add_u64 v[214:215], s[64:65], 0, v[134:135]
	s_add_i32 m0, s18, 0x2000
	s_nop 0
	global_load_lds_dwordx4 v[214:215], off
	v_lshl_add_u64 v[214:215], s[52:53], 0, v[128:129]
	s_mov_b32 m0, s11
	s_nop 0
	global_load_lds_dwordx4 v[214:215], off
	s_mov_b32 m0, s35
	s_nop 0
	global_load_lds_dwordx4 v[222:223], off
	s_waitcnt vmcnt(8)
	s_waitcnt lgkmcnt(0)
	s_setprio 1
	s_barrier
; #define PG8_STAGE(bufoff, gbase, voff) do { _Pragma("unroll") for (int _i = 0; _i < 2; ++_i) \
;         __builtin_amdgcn_global_load_lds((const unsigned*)((const char*)(gbase) + (voff)[_i]), (PG8_LAS unsigned*)(lds + (bufoff) + ldsw + _i * 8192), 16, 0, 0); } while (0)
; #define PG8_LDA(dst, b, h) do { _Pragma("unroll") for (int m = 0; m < 4; ++m) _Pragma("unroll") for (int k = 0; k < 2; ++k) dst[m][k] = *(const PG8_LAS bf16x8*)(lds + PG8_SA(b, h) + aoff + m * 2048 + k * 1024); } while (0)
; #define PG8_LDB(dst, b, h) do { _Pragma("unroll") for (int n = 0; n < 2; ++n) _Pragma("unroll") for (int k = 0; k < 2; ++k) dst[n][k] = *(const PG8_LAS bf16x8*)(lds + PG8_SB(b, h) + boff + n * 2048 + k * 1024); } while (0)
; #define PG8_MMA(ai, bj, At, Bt) do { __builtin_amdgcn_s_setprio(1); _Pragma("unroll") for (int m = 0; m < 4; ++m) _Pragma("unroll") for (int n = 0; n < 2; ++n) _Pragma("unroll") for (int k = 0; k < 2; ++k) \
;         acc[ai][bj][m][n] = __builtin_amdgcn_mfma_f32_16x16x32_bf16(Bt[n][k], At[m][k], acc[ai][bj][m][n], 0, 0, 0); __builtin_amdgcn_s_setprio(0); } while (0)
; #define PG8_WAIT_V(n) asm volatile("s_waitcnt vmcnt(" #n ")" ::: "memory")
; #define PG8_WAIT_L(n) asm volatile("s_waitcnt lgkmcnt(" #n ")" ::: "memory")
; #define PG8_BAR __builtin_amdgcn_s_barrier()
; #define PG8_SCHED __builtin_amdgcn_sched_barrier(0)
; template <class Epi, class Sched, bool ALIGN_EPI = false, bool SP2 = false>
; __device__ __forceinline__ void gemm_phase(PG8_LAS unsigned char* lds, const Gemm g, const Sched& S, const Epi& E) {
;     ...
;             PG8_LDA(At, 0, 1); PG8_STAGE(PG8_SB(0, 0), b2, voffB); PG8_STAGE(PG8_SB(0, 1), b2 + hstep, voffB); PG8_STAGE(PG8_SA(0, 0), a2, voffA);
;             PG8_WAIT_V(8); PG8_WAIT_L(0); PG8_BAR; PG8_MMA(1, 0, At, B0); PG8_MMA(1, 1, At, B1); PG8_BAR; PG8_SCHED;
;             PG8_LDB(B0, 1, 0); PG8_LDB(B1, 1, 1); PG8_SCHED; PG8_LDA(At, 1, 0); PG8_STAGE(PG8_SA(0, 1), a2 + hstep, voffA);
;             PG8_WAIT_V(8); PG8_WAIT_L(0); PG8_BAR; PG8_MMA(0, 0, At, B0); PG8_MMA(0, 1, At, B1); PG8_BAR; PG8_SCHED;
	v_mfma_f32_16x16x32_bf16 v[60:63], v[142:145], v[178:181], v[60:63]
	v_mfma_f32_16x16x32_bf16 v[56:59], v[150:153], v[178:181], v[56:59]
	v_mfma_f32_16x16x32_bf16 v[44:47], v[142:145], v[186:189], v[44:47]
	v_mfma_f32_16x16x32_bf16 v[40:43], v[150:153], v[186:189], v[40:43]
	v_mfma_f32_16x16x32_bf16 v[28:31], v[142:145], v[194:197], v[28:31]
	v_mfma_f32_16x16x32_bf16 v[24:27], v[150:153], v[194:197], v[24:27]
	v_mfma_f32_16x16x32_bf16 v[12:15], v[142:145], v[202:205], v[12:15]
	v_mfma_f32_16x16x32_bf16 v[8:11], v[150:153], v[202:205], v[8:11]
	v_mfma_f32_16x16x32_bf16 v[60:63], v[146:149], v[182:185], v[60:63]
	v_mfma_f32_16x16x32_bf16 v[56:59], v[158:161], v[182:185], v[56:59]
	v_mfma_f32_16x16x32_bf16 v[44:47], v[146:149], v[190:193], v[44:47]
	v_mfma_f32_16x16x32_bf16 v[40:43], v[158:161], v[190:193], v[40:43]
	v_mfma_f32_16x16x32_bf16 v[28:31], v[146:149], v[198:201], v[28:31]
	v_mfma_f32_16x16x32_bf16 v[24:27], v[158:161], v[198:201], v[24:27]
	v_mfma_f32_16x16x32_bf16 v[12:15], v[146:149], v[218:221], v[12:15]
	v_mfma_f32_16x16x32_bf16 v[8:11], v[158:161], v[218:221], v[8:11]
	s_setprio 0
	s_setprio 1
	v_mfma_f32_16x16x32_bf16 v[52:55], v[162:165], v[178:181], v[52:55]
	v_mfma_f32_16x16x32_bf16 v[48:51], v[170:173], v[178:181], v[48:51]
	v_mfma_f32_16x16x32_bf16 v[36:39], v[162:165], v[186:189], v[36:39]
	v_mfma_f32_16x16x32_bf16 v[32:35], v[170:173], v[186:189], v[32:35]
	v_mfma_f32_16x16x32_bf16 v[20:23], v[162:165], v[194:197], v[20:23]
	v_mfma_f32_16x16x32_bf16 v[16:19], v[170:173], v[194:197], v[16:19]
	v_mfma_f32_16x16x32_bf16 v[4:7], v[162:165], v[202:205], v[4:7]
	v_mfma_f32_16x16x32_bf16 v[0:3], v[170:173], v[202:205], v[0:3]
	v_mfma_f32_16x16x32_bf16 v[52:55], v[166:169], v[182:185], v[52:55]
	v_mfma_f32_16x16x32_bf16 v[48:51], v[174:177], v[182:185], v[48:51]
	v_mfma_f32_16x16x32_bf16 v[36:39], v[166:169], v[190:193], v[36:39]
	v_mfma_f32_16x16x32_bf16 v[32:35], v[174:177], v[190:193], v[32:35]
	v_mfma_f32_16x16x32_bf16 v[20:23], v[166:169], v[198:201], v[20:23]
	v_mfma_f32_16x16x32_bf16 v[16:19], v[174:177], v[198:201], v[16:19]
	v_mfma_f32_16x16x32_bf16 v[4:7], v[166:169], v[218:221], v[4:7]
	v_mfma_f32_16x16x32_bf16 v[0:3], v[174:177], v[218:221], v[0:3]
	s_setprio 0
	s_barrier
	s_add_i32 s18, 0, 0x18000
	s_add_i32 s19, 0, 0x1c000
	v_add_u32_e32 v158, s18, v155
	v_add_u32_e32 v174, s19, v155
	ds_read_b128 v[142:145], v158
	ds_read_b128 v[146:149], v158 offset:1024
	ds_read_b128 v[150:153], v158 offset:2048
	ds_read_b128 v[158:161], v158 offset:3072
	ds_read_b128 v[162:165], v174
	ds_read_b128 v[166:169], v174 offset:1024
	ds_read_b128 v[170:173], v174 offset:2048
	ds_read_b128 v[174:177], v174 offset:3072
	s_add_u32 s52, s52, 0x40000
	s_addc_u32 s53, s53, 0
	s_mov_b32 m0, s54
	v_lshl_add_u64 v[224:225], s[52:53], 0, v[128:129]
	ds_read_b128 v[178:181], v157 offset:32768
	ds_read_b128 v[182:185], v157 offset:33792
	ds_read_b128 v[186:189], v157 offset:34816
	ds_read_b128 v[190:193], v157 offset:35840
	ds_read_b128 v[194:197], v157 offset:36864
	ds_read_b128 v[198:201], v157 offset:37888
	ds_read_b128 v[202:205], v157 offset:38912
	ds_read_b128 v[218:221], v157 offset:39936
	global_load_lds_dwordx4 v[224:225], off
	v_lshl_add_u64 v[224:225], s[52:53], 0, v[132:133]
	s_mov_b32 m0, s55
	s_nop 0
	global_load_lds_dwordx4 v[224:225], off
	s_waitcnt vmcnt(8)
	s_waitcnt lgkmcnt(0)
	s_setprio 1
	s_barrier
	v_mfma_f32_16x16x32_bf16 v[124:127], v[142:145], v[178:181], v[124:127]
	v_mfma_f32_16x16x32_bf16 v[120:123], v[150:153], v[178:181], v[120:123]
	v_mfma_f32_16x16x32_bf16 v[108:111], v[142:145], v[186:189], v[108:111]
	v_mfma_f32_16x16x32_bf16 v[104:107], v[150:153], v[186:189], v[104:107]
	v_mfma_f32_16x16x32_bf16 v[92:95], v[142:145], v[194:197], v[92:95]
	v_mfma_f32_16x16x32_bf16 v[88:91], v[150:153], v[194:197], v[88:91]
	v_mfma_f32_16x16x32_bf16 v[76:79], v[142:145], v[202:205], v[76:79]
	v_mfma_f32_16x16x32_bf16 v[72:75], v[150:153], v[202:205], v[72:75]
	v_mfma_f32_16x16x32_bf16 v[124:127], v[146:149], v[182:185], v[124:127]
	v_mfma_f32_16x16x32_bf16 v[120:123], v[158:161], v[182:185], v[120:123]
	v_mfma_f32_16x16x32_bf16 v[108:111], v[146:149], v[190:193], v[108:111]
	v_mfma_f32_16x16x32_bf16 v[104:107], v[158:161], v[190:193], v[104:107]
	v_mfma_f32_16x16x32_bf16 v[92:95], v[146:149], v[198:201], v[92:95]
	v_mfma_f32_16x16x32_bf16 v[88:91], v[158:161], v[198:201], v[88:91]
	v_mfma_f32_16x16x32_bf16 v[76:79], v[146:149], v[218:221], v[76:79]
	v_mfma_f32_16x16x32_bf16 v[72:75], v[158:161], v[218:221], v[72:75]
	s_setprio 0
	s_setprio 1
	v_mfma_f32_16x16x32_bf16 v[116:119], v[162:165], v[178:181], v[116:119]
	v_mfma_f32_16x16x32_bf16 v[112:115], v[170:173], v[178:181], v[112:115]
	v_mfma_f32_16x16x32_bf16 v[100:103], v[162:165], v[186:189], v[100:103]
	v_mfma_f32_16x16x32_bf16 v[96:99], v[170:173], v[186:189], v[96:99]
	v_mfma_f32_16x16x32_bf16 v[84:87], v[162:165], v[194:197], v[84:87]
	v_mfma_f32_16x16x32_bf16 v[80:83], v[170:173], v[194:197], v[80:83]
	v_mfma_f32_16x16x32_bf16 v[68:71], v[162:165], v[202:205], v[68:71]
	v_mfma_f32_16x16x32_bf16 v[64:67], v[170:173], v[202:205], v[64:67]
	v_mfma_f32_16x16x32_bf16 v[116:119], v[166:169], v[182:185], v[116:119]
	v_mfma_f32_16x16x32_bf16 v[112:115], v[174:177], v[182:185], v[112:115]
	v_mfma_f32_16x16x32_bf16 v[100:103], v[166:169], v[190:193], v[100:103]
	v_mfma_f32_16x16x32_bf16 v[96:99], v[174:177], v[190:193], v[96:99]
	v_mfma_f32_16x16x32_bf16 v[84:87], v[166:169], v[198:201], v[84:87]
	v_mfma_f32_16x16x32_bf16 v[80:83], v[174:177], v[198:201], v[80:83]
	v_mfma_f32_16x16x32_bf16 v[68:71], v[166:169], v[218:221], v[68:71]
	v_mfma_f32_16x16x32_bf16 v[64:67], v[174:177], v[218:221], v[64:67]
	s_setprio 0
	s_barrier
; #define PG8_STAGE(bufoff, gbase, voff) do { _Pragma("unroll") for (int _i = 0; _i < 2; ++_i) \
;         __builtin_amdgcn_global_load_lds((const unsigned*)((const char*)(gbase) + (voff)[_i]), (PG8_LAS unsigned*)(lds + (bufoff) + ldsw + _i * 8192), 16, 0, 0); } while (0)
; #define PG8_LDA(dst, b, h) do { _Pragma("unroll") for (int m = 0; m < 4; ++m) _Pragma("unroll") for (int k = 0; k < 2; ++k) dst[m][k] = *(const PG8_LAS bf16x8*)(lds + PG8_SA(b, h) + aoff + m * 2048 + k * 1024); } while (0)
; #define PG8_LDB(dst, b, h) do { _Pragma("unroll") for (int n = 0; n < 2; ++n) _Pragma("unroll") for (int k = 0; k < 2; ++k) dst[n][k] = *(const PG8_LAS bf16x8*)(lds + PG8_SB(b, h) + boff + n * 2048 + k * 1024); } while (0)
; #define PG8_MMA(ai, bj, At, Bt) do { __builtin_amdgcn_s_setprio(1); _Pragma("unroll") for (int m = 0; m < 4; ++m) _Pragma("unroll") for (int n = 0; n < 2; ++n) _Pragma("unroll") for (int k = 0; k < 2; ++k) \
;         acc[ai][bj][m][n] = __builtin_amdgcn_mfma_f32_16x16x32_bf16(Bt[n][k], At[m][k], acc[ai][bj][m][n], 0, 0, 0); __builtin_amdgcn_s_setprio(0); } while (0)
; #define PG8_WAIT_V(n) asm volatile("s_waitcnt vmcnt(" #n ")" ::: "memory")
; #define PG8_WAIT_L(n) asm volatile("s_waitcnt lgkmcnt(" #n ")" ::: "memory")
; #define PG8_BAR __builtin_amdgcn_s_barrier()
; #define PG8_SCHED __builtin_amdgcn_sched_barrier(0)
; template <class Epi, class Sched, bool ALIGN_EPI = false, bool SP2 = false>
; __device__ __forceinline__ void gemm_phase(PG8_LAS unsigned char* lds, const Gemm g, const Sched& S, const Epi& E) {
;     ...
;             PG8_LDB(B0, 1, 0); PG8_LDB(B1, 1, 1); PG8_SCHED; PG8_LDA(At, 1, 0); PG8_STAGE(PG8_SA(0, 1), a2 + hstep, voffA);
;             PG8_WAIT_V(8); PG8_WAIT_L(0); PG8_BAR; PG8_MMA(0, 0, At, B0); PG8_MMA(0, 1, At, B1); PG8_BAR; PG8_SCHED;
;             PG8_LDA(At, 1, 1); PG8_STAGE(PG8_SB(1, 0), b3, voffB); PG8_STAGE(PG8_SB(1, 1), b3 + hstep, voffB); PG8_STAGE(PG8_SA(1, 0), a3, voffA);
;             PG8_WAIT_V(8); PG8_WAIT_L(0); PG8_BAR; PG8_MMA(1, 0, At, B0); PG8_MMA(1, 1, At, B1); PG8_BAR; PG8_SCHED;
	s_add_i32 s18, s18, s31
	v_lshl_add_u64 v[206:207], v[206:207], 0, s[24:25]
	s_mov_b32 m0, s18
	ds_read_b128 v[178:181], v157 offset:49152
	ds_read_b128 v[182:185], v157 offset:50176
	ds_read_b128 v[186:189], v157 offset:51200
	ds_read_b128 v[190:193], v157 offset:52224
	ds_read_b128 v[194:197], v157 offset:53248
	ds_read_b128 v[198:201], v157 offset:54272
	ds_read_b128 v[202:205], v157 offset:55296
	ds_read_b128 v[218:221], v157 offset:56320
	global_load_lds_dwordx4 v[206:207], off
	s_add_i32 m0, s18, 0x2000
	s_add_u32 s8, s8, 0x40080
	v_lshl_add_u64 v[206:207], v[212:213], 0, s[24:25]
	s_addc_u32 s9, s9, 0
	s_add_i32 s18, s19, s31
	global_load_lds_dwordx4 v[206:207], off
	v_lshl_add_u64 v[206:207], s[8:9], 0, v[130:131]
	s_mov_b32 m0, s18
	s_nop 0
	global_load_lds_dwordx4 v[206:207], off
	v_lshl_add_u64 v[206:207], s[8:9], 0, v[134:135]
	s_add_i32 m0, s18, 0x2000
	s_nop 0
	global_load_lds_dwordx4 v[206:207], off
	v_lshl_add_u64 v[206:207], v[214:215], 0, s[24:25]
	s_mov_b32 m0, s57
	s_nop 0
	global_load_lds_dwordx4 v[206:207], off
	v_lshl_add_u64 v[206:207], v[222:223], 0, s[24:25]
	s_mov_b32 m0, s58
	s_nop 0
	global_load_lds_dwordx4 v[206:207], off
	s_waitcnt vmcnt(8)
	s_waitcnt lgkmcnt(0)
	s_setprio 1
	s_barrier
	v_mfma_f32_16x16x32_bf16 v[60:63], v[142:145], v[178:181], v[60:63]
	v_mfma_f32_16x16x32_bf16 v[56:59], v[150:153], v[178:181], v[56:59]
	v_mfma_f32_16x16x32_bf16 v[44:47], v[142:145], v[186:189], v[44:47]
	v_mfma_f32_16x16x32_bf16 v[40:43], v[150:153], v[186:189], v[40:43]
	v_mfma_f32_16x16x32_bf16 v[28:31], v[142:145], v[194:197], v[28:31]
	v_mfma_f32_16x16x32_bf16 v[24:27], v[150:153], v[194:197], v[24:27]
	v_mfma_f32_16x16x32_bf16 v[12:15], v[142:145], v[202:205], v[12:15]
	v_mfma_f32_16x16x32_bf16 v[8:11], v[150:153], v[202:205], v[8:11]
	v_mfma_f32_16x16x32_bf16 v[60:63], v[146:149], v[182:185], v[60:63]
	v_mfma_f32_16x16x32_bf16 v[56:59], v[158:161], v[182:185], v[56:59]
	v_mfma_f32_16x16x32_bf16 v[44:47], v[146:149], v[190:193], v[44:47]
	v_mfma_f32_16x16x32_bf16 v[40:43], v[158:161], v[190:193], v[40:43]
	v_mfma_f32_16x16x32_bf16 v[28:31], v[146:149], v[198:201], v[28:31]
	v_mfma_f32_16x16x32_bf16 v[24:27], v[158:161], v[198:201], v[24:27]
	v_mfma_f32_16x16x32_bf16 v[12:15], v[146:149], v[218:221], v[12:15]
	v_mfma_f32_16x16x32_bf16 v[8:11], v[158:161], v[218:221], v[8:11]
	s_setprio 0
	s_setprio 1
	v_mfma_f32_16x16x32_bf16 v[52:55], v[162:165], v[178:181], v[52:55]
	v_mfma_f32_16x16x32_bf16 v[48:51], v[170:173], v[178:181], v[48:51]
	v_mfma_f32_16x16x32_bf16 v[36:39], v[162:165], v[186:189], v[36:39]
	v_mfma_f32_16x16x32_bf16 v[32:35], v[170:173], v[186:189], v[32:35]
	v_mfma_f32_16x16x32_bf16 v[20:23], v[162:165], v[194:197], v[20:23]
	v_mfma_f32_16x16x32_bf16 v[16:19], v[170:173], v[194:197], v[16:19]
	v_mfma_f32_16x16x32_bf16 v[4:7], v[162:165], v[202:205], v[4:7]
	v_mfma_f32_16x16x32_bf16 v[0:3], v[170:173], v[202:205], v[0:3]
	v_mfma_f32_16x16x32_bf16 v[52:55], v[166:169], v[182:185], v[52:55]
	v_mfma_f32_16x16x32_bf16 v[48:51], v[174:177], v[182:185], v[48:51]
	v_mfma_f32_16x16x32_bf16 v[36:39], v[166:169], v[190:193], v[36:39]
	v_mfma_f32_16x16x32_bf16 v[32:35], v[174:177], v[190:193], v[32:35]
	v_mfma_f32_16x16x32_bf16 v[20:23], v[166:169], v[198:201], v[20:23]
	v_mfma_f32_16x16x32_bf16 v[16:19], v[174:177], v[198:201], v[16:19]
	v_mfma_f32_16x16x32_bf16 v[4:7], v[166:169], v[218:221], v[4:7]
	v_mfma_f32_16x16x32_bf16 v[0:3], v[174:177], v[218:221], v[0:3]
	s_setprio 0
	s_barrier
	s_add_i32 s63, s63, 2
	s_add_u32 s6, s6, 0x100
	s_addc_u32 s7, s7, 0
	s_add_u32 s47, s47, 0x100
	s_addc_u32 s62, s62, 0
	s_cmp_gt_u32 s63, 13
	s_cbranch_scc0 .LBB0_334
	s_and_b64 vcc, exec, s[26:27]
	s_cbranch_vccz .LBB0_337
	s_barrier
